# GEMM K-loops without per-cluster setprio; 64-bit acc zeroing; EP_U epilogue hand-scheduled, tile order specialised
# speedup vs baseline: 1.0437x; 1.0372x over previous
.LBB0_276:
	s_add_u32 s3, s20, 0x100
	s_addc_u32 s34, s21, 0
	s_add_u32 s8, s30, 0x80
	v_mov_b64_e32 v[0:1], 0
	v_mov_b64_e32 v[2:3], 0
	v_mov_b64_e32 v[4:5], 0
	v_mov_b64_e32 v[6:7], 0
	v_mov_b64_e32 v[8:9], 0
	v_mov_b64_e32 v[10:11], 0
	v_mov_b64_e32 v[12:13], 0
	v_mov_b64_e32 v[14:15], 0
	v_mov_b64_e32 v[16:17], 0
	v_mov_b64_e32 v[18:19], 0
	v_mov_b64_e32 v[20:21], 0
	v_mov_b64_e32 v[22:23], 0
	v_mov_b64_e32 v[24:25], 0
	v_mov_b64_e32 v[26:27], 0
	v_mov_b64_e32 v[28:29], 0
	v_mov_b64_e32 v[30:31], 0
	v_mov_b64_e32 v[32:33], 0
	v_mov_b64_e32 v[34:35], 0
	v_mov_b64_e32 v[36:37], 0
	v_mov_b64_e32 v[38:39], 0
	v_mov_b64_e32 v[40:41], 0
	v_mov_b64_e32 v[42:43], 0
	v_mov_b64_e32 v[44:45], 0
	v_mov_b64_e32 v[46:47], 0
	v_mov_b64_e32 v[48:49], 0
	v_mov_b64_e32 v[50:51], 0
	v_mov_b64_e32 v[52:53], 0
	v_mov_b64_e32 v[54:55], 0
	v_mov_b64_e32 v[56:57], 0
	v_mov_b64_e32 v[58:59], 0
	v_mov_b64_e32 v[60:61], 0
	v_mov_b64_e32 v[62:63], 0
	v_mov_b64_e32 v[64:65], 0
	v_mov_b64_e32 v[66:67], 0
	v_mov_b64_e32 v[68:69], 0
	v_mov_b64_e32 v[70:71], 0
	v_mov_b64_e32 v[72:73], 0
	v_mov_b64_e32 v[74:75], 0
	v_mov_b64_e32 v[76:77], 0
	v_mov_b64_e32 v[78:79], 0
	v_mov_b64_e32 v[80:81], 0
	v_mov_b64_e32 v[82:83], 0
	v_mov_b64_e32 v[84:85], 0
	v_mov_b64_e32 v[86:87], 0
	v_mov_b64_e32 v[88:89], 0
	v_mov_b64_e32 v[90:91], 0
	v_mov_b64_e32 v[92:93], 0
	v_mov_b64_e32 v[94:95], 0
	v_mov_b64_e32 v[96:97], 0
	v_mov_b64_e32 v[98:99], 0
	v_mov_b64_e32 v[100:101], 0
	v_mov_b64_e32 v[102:103], 0
	v_mov_b64_e32 v[104:105], 0
	v_mov_b64_e32 v[106:107], 0
	v_mov_b64_e32 v[108:109], 0
	v_mov_b64_e32 v[110:111], 0
	v_mov_b64_e32 v[112:113], 0
	v_mov_b64_e32 v[114:115], 0
	v_mov_b64_e32 v[116:117], 0
	v_mov_b64_e32 v[118:119], 0
	v_mov_b64_e32 v[120:121], 0
	v_mov_b64_e32 v[122:123], 0
	v_mov_b64_e32 v[124:125], 0
	v_mov_b64_e32 v[126:127], 0
	s_addc_u32 s9, s31, 0
	s_mov_b32 s20, 0
	s_waitcnt vmcnt(0)
.LBB0_277:
	v_add_u32_e32 v150, s87, v171
	ds_read_b128 v[128:131], v150
	ds_read_b128 v[132:135], v150 offset:1024
	ds_read_b128 v[136:139], v150 offset:2048
	ds_read_b128 v[150:153], v150 offset:3072
	s_add_i32 s35, s20, 2
	s_add_u32 s30, s8, 0x80
	s_addc_u32 s21, s9, 0
	s_cmp_eq_u32 s38, s20
	s_cselect_b32 s20, s76, s30
	s_cselect_b32 s21, s77, s21
	s_cselect_b32 s31, s11, s34
	s_cselect_b32 s30, s10, s3
	v_lshl_add_u64 v[158:159], s[8:9], 0, v[148:149]
	s_add_i32 m0, s26, 0xc000
	ds_read_b128 v[154:157], v173
	ds_read_b128 v[166:169], v173 offset:1024
	ds_read_b128 v[174:177], v173 offset:2048
	ds_read_b128 v[178:181], v173 offset:3072
	ds_read_b128 v[182:185], v173 offset:4096
	ds_read_b128 v[186:189], v173 offset:5120
	ds_read_b128 v[190:193], v173 offset:6144
	ds_read_b128 v[194:197], v173 offset:7168
	global_load_lds_dwordx4 v[158:159], off
	v_lshl_add_u64 v[158:159], s[8:9], 0, v[146:147]
	s_add_i32 m0, s26, 0xe000
	s_nop 0
	global_load_lds_dwordx4 v[158:159], off
	s_waitcnt lgkmcnt(8)
	s_barrier
	s_waitcnt lgkmcnt(0)
	s_waitcnt lgkmcnt(0)
	v_mfma_f32_16x16x32_bf16 v[124:127], v[128:131], v[154:157], v[124:127]
	v_mfma_f32_16x16x32_bf16 v[120:123], v[136:139], v[154:157], v[120:123]
	v_mfma_f32_16x16x32_bf16 v[112:115], v[128:131], v[174:177], v[112:115]
	v_mfma_f32_16x16x32_bf16 v[108:111], v[136:139], v[174:177], v[108:111]
	v_mfma_f32_16x16x32_bf16 v[100:103], v[128:131], v[182:185], v[100:103]
	v_mfma_f32_16x16x32_bf16 v[92:95], v[136:139], v[182:185], v[92:95]
	v_mfma_f32_16x16x32_bf16 v[84:87], v[128:131], v[190:193], v[84:87]
	v_mfma_f32_16x16x32_bf16 v[76:79], v[136:139], v[190:193], v[76:79]
	v_mfma_f32_16x16x32_bf16 v[124:127], v[132:135], v[166:169], v[124:127]
	v_mfma_f32_16x16x32_bf16 v[120:123], v[150:153], v[166:169], v[120:123]
	v_mfma_f32_16x16x32_bf16 v[112:115], v[132:135], v[178:181], v[112:115]
	v_mfma_f32_16x16x32_bf16 v[108:111], v[150:153], v[178:181], v[108:111]
	v_mfma_f32_16x16x32_bf16 v[100:103], v[132:135], v[186:189], v[100:103]
	v_mfma_f32_16x16x32_bf16 v[92:95], v[150:153], v[186:189], v[92:95]
	v_mfma_f32_16x16x32_bf16 v[84:87], v[132:135], v[194:197], v[84:87]
	v_mfma_f32_16x16x32_bf16 v[76:79], v[150:153], v[194:197], v[76:79]
	s_barrier
	s_add_i32 s52, 0, 0x14000
	v_add_u32_e32 v158, s52, v171
	s_add_i32 s78, s87, s23
	ds_read_b128 v[198:201], v158
	ds_read_b128 v[232:235], v158 offset:1024
	ds_read_b128 v[236:239], v158 offset:2048
	ds_read_b128 v[240:243], v158 offset:3072
	v_lshl_add_u64 v[158:159], s[30:31], 0, v[160:161]
	s_mov_b32 m0, s78
	v_lshl_add_u64 v[202:203], s[30:31], 0, v[144:145]
	global_load_lds_dwordx4 v[158:159], off
	s_add_i32 m0, s78, 0x2000
	s_nop 0
	global_load_lds_dwordx4 v[202:203], off
	s_barrier
	s_waitcnt lgkmcnt(0)
	s_waitcnt lgkmcnt(0)
	v_mfma_f32_16x16x32_bf16 v[116:119], v[198:201], v[154:157], v[116:119]
	v_mfma_f32_16x16x32_bf16 v[104:107], v[236:239], v[154:157], v[104:107]
	v_mfma_f32_16x16x32_bf16 v[96:99], v[198:201], v[174:177], v[96:99]
	v_mfma_f32_16x16x32_bf16 v[88:91], v[236:239], v[174:177], v[88:91]
	v_mfma_f32_16x16x32_bf16 v[80:83], v[198:201], v[182:185], v[80:83]
	v_mfma_f32_16x16x32_bf16 v[72:75], v[236:239], v[182:185], v[72:75]
	v_mfma_f32_16x16x32_bf16 v[68:71], v[198:201], v[190:193], v[68:71]
	v_mfma_f32_16x16x32_bf16 v[64:67], v[236:239], v[190:193], v[64:67]
	v_mfma_f32_16x16x32_bf16 v[116:119], v[232:235], v[166:169], v[116:119]
	v_mfma_f32_16x16x32_bf16 v[104:107], v[240:243], v[166:169], v[104:107]
	v_mfma_f32_16x16x32_bf16 v[96:99], v[232:235], v[178:181], v[96:99]
	v_mfma_f32_16x16x32_bf16 v[88:91], v[240:243], v[178:181], v[88:91]
	v_mfma_f32_16x16x32_bf16 v[80:83], v[232:235], v[186:189], v[80:83]
	v_mfma_f32_16x16x32_bf16 v[72:75], v[240:243], v[186:189], v[72:75]
	v_mfma_f32_16x16x32_bf16 v[68:71], v[232:235], v[194:197], v[68:71]
	v_mfma_f32_16x16x32_bf16 v[64:67], v[240:243], v[194:197], v[64:67]
	s_mov_b32 m0, s26
	v_lshl_add_u64 v[206:207], s[20:21], 0, v[140:141]
	s_barrier
	ds_read_b128 v[154:157], v173 offset:16384
	ds_read_b128 v[166:169], v173 offset:17408
	ds_read_b128 v[174:177], v173 offset:18432
	ds_read_b128 v[178:181], v173 offset:19456
	ds_read_b128 v[182:185], v173 offset:20480
	ds_read_b128 v[186:189], v173 offset:21504
	ds_read_b128 v[190:193], v173 offset:22528
	ds_read_b128 v[194:197], v173 offset:23552
	global_load_lds_dwordx4 v[206:207], off
	v_lshl_add_u64 v[210:211], s[20:21], 0, v[142:143]
	s_mov_b32 m0, s16
	s_nop 0
	global_load_lds_dwordx4 v[210:211], off
	s_barrier
	s_waitcnt lgkmcnt(0)
	s_waitcnt lgkmcnt(0)
	v_mfma_f32_16x16x32_bf16 v[60:63], v[128:131], v[154:157], v[60:63]
	v_mfma_f32_16x16x32_bf16 v[56:59], v[136:139], v[154:157], v[56:59]
	v_mfma_f32_16x16x32_bf16 v[52:55], v[128:131], v[174:177], v[52:55]
	v_mfma_f32_16x16x32_bf16 v[44:47], v[136:139], v[174:177], v[44:47]
	v_mfma_f32_16x16x32_bf16 v[36:39], v[128:131], v[182:185], v[36:39]
	v_mfma_f32_16x16x32_bf16 v[28:31], v[136:139], v[182:185], v[28:31]
	v_mfma_f32_16x16x32_bf16 v[20:23], v[128:131], v[190:193], v[20:23]
	v_mfma_f32_16x16x32_bf16 v[12:15], v[136:139], v[190:193], v[12:15]
	v_mfma_f32_16x16x32_bf16 v[60:63], v[132:135], v[166:169], v[60:63]
	v_mfma_f32_16x16x32_bf16 v[56:59], v[150:153], v[166:169], v[56:59]
	v_mfma_f32_16x16x32_bf16 v[52:55], v[132:135], v[178:181], v[52:55]
	v_mfma_f32_16x16x32_bf16 v[44:47], v[150:153], v[178:181], v[44:47]
	v_mfma_f32_16x16x32_bf16 v[36:39], v[132:135], v[186:189], v[36:39]
	v_mfma_f32_16x16x32_bf16 v[28:31], v[150:153], v[186:189], v[28:31]
	v_mfma_f32_16x16x32_bf16 v[20:23], v[132:135], v[194:197], v[20:23]
	v_mfma_f32_16x16x32_bf16 v[12:15], v[150:153], v[194:197], v[12:15]
	s_barrier
	s_add_u32 s30, s30, s64
	s_addc_u32 s31, s31, s65
	s_add_i32 s52, s52, s23
	v_lshl_add_u64 v[244:245], s[30:31], 0, v[160:161]
	s_mov_b32 m0, s52
	v_lshl_add_u64 v[246:247], s[30:31], 0, v[144:145]
	global_load_lds_dwordx4 v[244:245], off
	s_add_i32 m0, s52, 0x2000
	s_nop 0
	global_load_lds_dwordx4 v[246:247], off
	s_waitcnt vmcnt(6)
	s_barrier
	v_mfma_f32_16x16x32_bf16 v[48:51], v[198:201], v[154:157], v[48:51]
	v_mfma_f32_16x16x32_bf16 v[40:43], v[236:239], v[154:157], v[40:43]
	v_mfma_f32_16x16x32_bf16 v[32:35], v[198:201], v[174:177], v[32:35]
	v_mfma_f32_16x16x32_bf16 v[24:27], v[236:239], v[174:177], v[24:27]
	v_mfma_f32_16x16x32_bf16 v[16:19], v[198:201], v[182:185], v[16:19]
	v_mfma_f32_16x16x32_bf16 v[8:11], v[236:239], v[182:185], v[8:11]
	v_mfma_f32_16x16x32_bf16 v[4:7], v[198:201], v[190:193], v[4:7]
	v_mfma_f32_16x16x32_bf16 v[0:3], v[236:239], v[190:193], v[0:3]
	v_mfma_f32_16x16x32_bf16 v[48:51], v[232:235], v[166:169], v[48:51]
	v_mfma_f32_16x16x32_bf16 v[40:43], v[240:243], v[166:169], v[40:43]
	v_mfma_f32_16x16x32_bf16 v[32:35], v[232:235], v[178:181], v[32:35]
	v_mfma_f32_16x16x32_bf16 v[24:27], v[240:243], v[178:181], v[24:27]
	v_mfma_f32_16x16x32_bf16 v[16:19], v[232:235], v[186:189], v[16:19]
	v_mfma_f32_16x16x32_bf16 v[8:11], v[240:243], v[186:189], v[8:11]
	v_mfma_f32_16x16x32_bf16 v[4:7], v[232:235], v[194:197], v[4:7]
	v_mfma_f32_16x16x32_bf16 v[0:3], v[240:243], v[194:197], v[0:3]
	s_add_i32 s30, 0, 0x18000
	v_add_u32_e32 v150, s30, v171
	s_barrier
	ds_read_b128 v[128:131], v150
	ds_read_b128 v[132:135], v150 offset:1024
	ds_read_b128 v[136:139], v150 offset:2048
	ds_read_b128 v[150:153], v150 offset:3072
	s_add_u32 s20, s20, s64
	s_addc_u32 s21, s21, s65
	s_mov_b32 m0, s17
	v_lshl_add_u64 v[198:199], s[20:21], 0, v[140:141]
	ds_read_b128 v[154:157], v173 offset:32768
	ds_read_b128 v[166:169], v173 offset:33792
	ds_read_b128 v[174:177], v173 offset:34816
	ds_read_b128 v[178:181], v173 offset:35840
	ds_read_b128 v[182:185], v173 offset:36864
	ds_read_b128 v[186:189], v173 offset:37888
	ds_read_b128 v[190:193], v173 offset:38912
	ds_read_b128 v[194:197], v173 offset:39936
	global_load_lds_dwordx4 v[198:199], off
	v_lshl_add_u64 v[198:199], s[20:21], 0, v[142:143]
	s_mov_b32 m0, s27
	s_nop 0
	global_load_lds_dwordx4 v[198:199], off
	s_waitcnt lgkmcnt(8)
	s_barrier
	s_waitcnt lgkmcnt(0)
	s_waitcnt lgkmcnt(0)
	v_mfma_f32_16x16x32_bf16 v[124:127], v[128:131], v[154:157], v[124:127]
	v_mfma_f32_16x16x32_bf16 v[120:123], v[136:139], v[154:157], v[120:123]
	v_mfma_f32_16x16x32_bf16 v[112:115], v[128:131], v[174:177], v[112:115]
	v_mfma_f32_16x16x32_bf16 v[108:111], v[136:139], v[174:177], v[108:111]
	v_mfma_f32_16x16x32_bf16 v[100:103], v[128:131], v[182:185], v[100:103]
	v_mfma_f32_16x16x32_bf16 v[92:95], v[136:139], v[182:185], v[92:95]
	v_mfma_f32_16x16x32_bf16 v[84:87], v[128:131], v[190:193], v[84:87]
	v_mfma_f32_16x16x32_bf16 v[76:79], v[136:139], v[190:193], v[76:79]
	v_mfma_f32_16x16x32_bf16 v[124:127], v[132:135], v[166:169], v[124:127]
	v_mfma_f32_16x16x32_bf16 v[120:123], v[150:153], v[166:169], v[120:123]
	v_mfma_f32_16x16x32_bf16 v[112:115], v[132:135], v[178:181], v[112:115]
	v_mfma_f32_16x16x32_bf16 v[108:111], v[150:153], v[178:181], v[108:111]
	v_mfma_f32_16x16x32_bf16 v[100:103], v[132:135], v[186:189], v[100:103]
	v_mfma_f32_16x16x32_bf16 v[92:95], v[150:153], v[186:189], v[92:95]
	v_mfma_f32_16x16x32_bf16 v[84:87], v[132:135], v[194:197], v[84:87]
	v_mfma_f32_16x16x32_bf16 v[76:79], v[150:153], v[194:197], v[76:79]
	s_barrier
	s_add_i32 s20, 0, 0x1c000
	s_add_i32 s21, s30, s23
	v_add_u32_e32 v240, s20, v171
	v_lshl_add_u64 v[158:159], v[158:159], 0, s[96:97]
	s_mov_b32 m0, s21
	ds_read_b128 v[198:201], v240
	ds_read_b128 v[232:235], v240 offset:1024
	ds_read_b128 v[236:239], v240 offset:2048
	ds_read_b128 v[240:243], v240 offset:3072
	global_load_lds_dwordx4 v[158:159], off
	v_lshl_add_u64 v[158:159], v[202:203], 0, s[96:97]
	s_add_i32 m0, s21, 0x2000
	s_nop 0
	global_load_lds_dwordx4 v[158:159], off
	s_barrier
	s_waitcnt lgkmcnt(0)
	s_waitcnt lgkmcnt(0)
	v_mfma_f32_16x16x32_bf16 v[116:119], v[198:201], v[154:157], v[116:119]
	v_mfma_f32_16x16x32_bf16 v[104:107], v[236:239], v[154:157], v[104:107]
	v_mfma_f32_16x16x32_bf16 v[96:99], v[198:201], v[174:177], v[96:99]
	v_mfma_f32_16x16x32_bf16 v[88:91], v[236:239], v[174:177], v[88:91]
	v_mfma_f32_16x16x32_bf16 v[80:83], v[198:201], v[182:185], v[80:83]
	v_mfma_f32_16x16x32_bf16 v[72:75], v[236:239], v[182:185], v[72:75]
	v_mfma_f32_16x16x32_bf16 v[68:71], v[198:201], v[190:193], v[68:71]
	v_mfma_f32_16x16x32_bf16 v[64:67], v[236:239], v[190:193], v[64:67]
	v_mfma_f32_16x16x32_bf16 v[116:119], v[232:235], v[166:169], v[116:119]
	v_mfma_f32_16x16x32_bf16 v[104:107], v[240:243], v[166:169], v[104:107]
	v_mfma_f32_16x16x32_bf16 v[96:99], v[232:235], v[178:181], v[96:99]
	v_mfma_f32_16x16x32_bf16 v[88:91], v[240:243], v[178:181], v[88:91]
	v_mfma_f32_16x16x32_bf16 v[80:83], v[232:235], v[186:189], v[80:83]
	v_mfma_f32_16x16x32_bf16 v[72:75], v[240:243], v[186:189], v[72:75]
	v_mfma_f32_16x16x32_bf16 v[68:71], v[232:235], v[194:197], v[68:71]
	v_mfma_f32_16x16x32_bf16 v[64:67], v[240:243], v[194:197], v[64:67]
	s_mov_b32 m0, s28
	v_lshl_add_u64 v[158:159], v[206:207], 0, s[96:97]
	s_barrier
	ds_read_b128 v[154:157], v173 offset:49152
	ds_read_b128 v[166:169], v173 offset:50176
	ds_read_b128 v[174:177], v173 offset:51200
	ds_read_b128 v[178:181], v173 offset:52224
	ds_read_b128 v[182:185], v173 offset:53248
	ds_read_b128 v[186:189], v173 offset:54272
	ds_read_b128 v[190:193], v173 offset:55296
	ds_read_b128 v[194:197], v173 offset:56320
	global_load_lds_dwordx4 v[158:159], off
	v_lshl_add_u64 v[158:159], v[210:211], 0, s[96:97]
	s_mov_b32 m0, s29
	s_nop 0
	global_load_lds_dwordx4 v[158:159], off
	s_barrier
	s_waitcnt lgkmcnt(0)
	s_waitcnt lgkmcnt(0)
	v_mfma_f32_16x16x32_bf16 v[60:63], v[128:131], v[154:157], v[60:63]
	v_mfma_f32_16x16x32_bf16 v[56:59], v[136:139], v[154:157], v[56:59]
	v_mfma_f32_16x16x32_bf16 v[52:55], v[128:131], v[174:177], v[52:55]
	v_mfma_f32_16x16x32_bf16 v[44:47], v[136:139], v[174:177], v[44:47]
	v_mfma_f32_16x16x32_bf16 v[36:39], v[128:131], v[182:185], v[36:39]
	v_mfma_f32_16x16x32_bf16 v[28:31], v[136:139], v[182:185], v[28:31]
	v_mfma_f32_16x16x32_bf16 v[20:23], v[128:131], v[190:193], v[20:23]
	v_mfma_f32_16x16x32_bf16 v[12:15], v[136:139], v[190:193], v[12:15]
	v_mfma_f32_16x16x32_bf16 v[60:63], v[132:135], v[166:169], v[60:63]
	v_mfma_f32_16x16x32_bf16 v[56:59], v[150:153], v[166:169], v[56:59]
	v_mfma_f32_16x16x32_bf16 v[52:55], v[132:135], v[178:181], v[52:55]
	v_mfma_f32_16x16x32_bf16 v[44:47], v[150:153], v[178:181], v[44:47]
	v_mfma_f32_16x16x32_bf16 v[36:39], v[132:135], v[186:189], v[36:39]
	v_mfma_f32_16x16x32_bf16 v[28:31], v[150:153], v[186:189], v[28:31]
	v_mfma_f32_16x16x32_bf16 v[20:23], v[132:135], v[194:197], v[20:23]
	v_mfma_f32_16x16x32_bf16 v[12:15], v[150:153], v[194:197], v[12:15]
	s_barrier
	s_add_i32 s20, s20, s23
	v_lshl_add_u64 v[128:129], v[244:245], 0, s[96:97]
	s_mov_b32 m0, s20
	s_nop 0
	global_load_lds_dwordx4 v[128:129], off
	v_lshl_add_u64 v[128:129], v[246:247], 0, s[96:97]
	s_add_i32 m0, s20, 0x2000
	s_nop 0
	global_load_lds_dwordx4 v[128:129], off
	s_waitcnt vmcnt(6)
	s_barrier
	v_mfma_f32_16x16x32_bf16 v[48:51], v[198:201], v[154:157], v[48:51]
	v_mfma_f32_16x16x32_bf16 v[40:43], v[236:239], v[154:157], v[40:43]
	v_mfma_f32_16x16x32_bf16 v[32:35], v[198:201], v[174:177], v[32:35]
	v_mfma_f32_16x16x32_bf16 v[24:27], v[236:239], v[174:177], v[24:27]
	v_mfma_f32_16x16x32_bf16 v[16:19], v[198:201], v[182:185], v[16:19]
	v_mfma_f32_16x16x32_bf16 v[8:11], v[236:239], v[182:185], v[8:11]
	v_mfma_f32_16x16x32_bf16 v[4:7], v[198:201], v[190:193], v[4:7]
	v_mfma_f32_16x16x32_bf16 v[0:3], v[236:239], v[190:193], v[0:3]
	v_mfma_f32_16x16x32_bf16 v[48:51], v[232:235], v[166:169], v[48:51]
	v_mfma_f32_16x16x32_bf16 v[40:43], v[240:243], v[166:169], v[40:43]
	v_mfma_f32_16x16x32_bf16 v[32:35], v[232:235], v[178:181], v[32:35]
	v_mfma_f32_16x16x32_bf16 v[24:27], v[240:243], v[178:181], v[24:27]
	v_mfma_f32_16x16x32_bf16 v[16:19], v[232:235], v[186:189], v[16:19]
	v_mfma_f32_16x16x32_bf16 v[8:11], v[240:243], v[186:189], v[8:11]
	v_mfma_f32_16x16x32_bf16 v[4:7], v[232:235], v[194:197], v[4:7]
	v_mfma_f32_16x16x32_bf16 v[0:3], v[240:243], v[194:197], v[0:3]
	s_add_u32 s3, s3, 0x100
	s_addc_u32 s34, s34, 0
	s_add_u32 s8, s8, 0x100
	s_addc_u32 s9, s9, 0
	s_cmp_ge_i32 s35, s41
	s_mov_b32 s20, s35
	s_barrier
	s_cbranch_scc0 .LBB0_277
	v_readlane_b32 s8, v254, 5
	v_mov_b32 v128, s8
	v_readlane_b32 s9, v254, 6
	v_readfirstlane_b32 s89, v128
	v_mov_b32 v128, s9
	s_add_u32 s3, s89, 0x14400000
	v_readfirstlane_b32 s90, v128
	s_addc_u32 s88, s90, 0
	s_add_u32 s8, s89, 0xc400000
	s_addc_u32 s9, s90, 0
	s_mov_b64 s[30:31], -1
	s_mov_b64 s[20:21], 0
	s_cmp_lt_i32 s2, 5
	s_mov_b64 s[78:79], 0
	s_mov_b64 s[82:83], 0
	s_cbranch_scc1 .LBB0_282
	s_mov_b64 s[82:83], -1
	s_mov_b64 s[30:31], 0
	s_cmp_gt_i32 s2, 5
	s_cbranch_scc0 .LBB0_282
	s_cmp_gt_i32 s2, 6
	s_cbranch_scc0 .LBB0_303
	s_cmp_eq_u32 s2, 7
	s_cselect_b64 s[82:83], -1, 0

.LBB0_347:
	s_add_u32 s38, s20, 0x100
	s_addc_u32 s39, s21, 0
	s_add_u32 vcc_lo, s84, 0x80
	v_mov_b64_e32 v[0:1], 0
	v_mov_b64_e32 v[2:3], 0
	v_mov_b64_e32 v[4:5], 0
	v_mov_b64_e32 v[6:7], 0
	v_mov_b64_e32 v[8:9], 0
	v_mov_b64_e32 v[10:11], 0
	v_mov_b64_e32 v[12:13], 0
	v_mov_b64_e32 v[14:15], 0
	v_mov_b64_e32 v[16:17], 0
	v_mov_b64_e32 v[18:19], 0
	v_mov_b64_e32 v[20:21], 0
	v_mov_b64_e32 v[22:23], 0
	v_mov_b64_e32 v[24:25], 0
	v_mov_b64_e32 v[26:27], 0
	v_mov_b64_e32 v[28:29], 0
	v_mov_b64_e32 v[30:31], 0
	v_mov_b64_e32 v[32:33], 0
	v_mov_b64_e32 v[34:35], 0
	v_mov_b64_e32 v[36:37], 0
	v_mov_b64_e32 v[38:39], 0
	v_mov_b64_e32 v[40:41], 0
	v_mov_b64_e32 v[42:43], 0
	v_mov_b64_e32 v[44:45], 0
	v_mov_b64_e32 v[46:47], 0
	v_mov_b64_e32 v[48:49], 0
	v_mov_b64_e32 v[50:51], 0
	v_mov_b64_e32 v[52:53], 0
	v_mov_b64_e32 v[54:55], 0
	v_mov_b64_e32 v[56:57], 0
	v_mov_b64_e32 v[58:59], 0
	v_mov_b64_e32 v[60:61], 0
	v_mov_b64_e32 v[62:63], 0
	v_mov_b64_e32 v[64:65], 0
	v_mov_b64_e32 v[66:67], 0
	v_mov_b64_e32 v[68:69], 0
	v_mov_b64_e32 v[70:71], 0
	v_mov_b64_e32 v[72:73], 0
	v_mov_b64_e32 v[74:75], 0
	v_mov_b64_e32 v[76:77], 0
	v_mov_b64_e32 v[78:79], 0
	v_mov_b64_e32 v[80:81], 0
	v_mov_b64_e32 v[82:83], 0
	v_mov_b64_e32 v[84:85], 0
	v_mov_b64_e32 v[86:87], 0
	v_mov_b64_e32 v[88:89], 0
	v_mov_b64_e32 v[90:91], 0
	v_mov_b64_e32 v[92:93], 0
	v_mov_b64_e32 v[94:95], 0
	v_mov_b64_e32 v[96:97], 0
	v_mov_b64_e32 v[98:99], 0
	v_mov_b64_e32 v[100:101], 0
	v_mov_b64_e32 v[102:103], 0
	v_mov_b64_e32 v[104:105], 0
	v_mov_b64_e32 v[106:107], 0
	v_mov_b64_e32 v[108:109], 0
	v_mov_b64_e32 v[110:111], 0
	v_mov_b64_e32 v[112:113], 0
	v_mov_b64_e32 v[114:115], 0
	v_mov_b64_e32 v[116:117], 0
	v_mov_b64_e32 v[118:119], 0
	v_mov_b64_e32 v[120:121], 0
	v_mov_b64_e32 v[122:123], 0
	v_mov_b64_e32 v[124:125], 0
	v_mov_b64_e32 v[126:127], 0
	s_addc_u32 vcc_hi, s85, 0
	s_mov_b32 s20, 0
.LBB0_348:
	v_add_u32_e32 v148, s87, v151
	ds_read_b128 v[128:131], v148
	ds_read_b128 v[132:135], v148 offset:1024
	ds_read_b128 v[156:159], v148 offset:2048
	ds_read_b128 v[166:169], v148 offset:3072
	s_add_i32 s42, s20, 2
	s_add_u32 s16, vcc_lo, 0x80
	s_addc_u32 s21, vcc_hi, 0
	s_cmp_eq_u32 s48, s20
	s_cselect_b32 s20, s94, s16
	s_cselect_b32 s21, s95, s21
	s_cselect_b32 s35, s11, s39
	s_cselect_b32 s34, s10, s38
	v_lshl_add_u64 v[148:149], vcc, 0, v[146:147]
	s_add_i32 m0, s22, 0xc000
	ds_read_b128 v[170:173], v154
	ds_read_b128 v[174:177], v154 offset:1024
	ds_read_b128 v[178:181], v154 offset:2048
	ds_read_b128 v[182:185], v154 offset:3072
	ds_read_b128 v[186:189], v154 offset:4096
	ds_read_b128 v[190:193], v154 offset:5120
	ds_read_b128 v[194:197], v154 offset:6144
	ds_read_b128 v[198:201], v154 offset:7168
	global_load_lds_dwordx4 v[148:149], off
	v_lshl_add_u64 v[148:149], vcc, 0, v[144:145]
	s_add_i32 m0, s22, 0xe000
	s_nop 0
	global_load_lds_dwordx4 v[148:149], off
	s_waitcnt lgkmcnt(8)
	s_barrier
	s_waitcnt lgkmcnt(0)
	s_waitcnt lgkmcnt(0)
	v_mfma_f32_16x16x32_bf16 v[124:127], v[128:131], v[170:173], v[124:127]
	v_mfma_f32_16x16x32_bf16 v[120:123], v[156:159], v[170:173], v[120:123]
	v_mfma_f32_16x16x32_bf16 v[108:111], v[128:131], v[178:181], v[108:111]
	v_mfma_f32_16x16x32_bf16 v[104:107], v[156:159], v[178:181], v[104:107]
	v_mfma_f32_16x16x32_bf16 v[92:95], v[128:131], v[186:189], v[92:95]
	v_mfma_f32_16x16x32_bf16 v[88:91], v[156:159], v[186:189], v[88:91]
	v_mfma_f32_16x16x32_bf16 v[76:79], v[128:131], v[194:197], v[76:79]
	v_mfma_f32_16x16x32_bf16 v[72:75], v[156:159], v[194:197], v[72:75]
	v_mfma_f32_16x16x32_bf16 v[124:127], v[132:135], v[174:177], v[124:127]
	v_mfma_f32_16x16x32_bf16 v[120:123], v[166:169], v[174:177], v[120:123]
	v_mfma_f32_16x16x32_bf16 v[108:111], v[132:135], v[182:185], v[108:111]
	v_mfma_f32_16x16x32_bf16 v[104:107], v[166:169], v[182:185], v[104:107]
	v_mfma_f32_16x16x32_bf16 v[92:95], v[132:135], v[190:193], v[92:95]
	v_mfma_f32_16x16x32_bf16 v[88:91], v[166:169], v[190:193], v[88:91]
	v_mfma_f32_16x16x32_bf16 v[76:79], v[132:135], v[198:201], v[76:79]
	v_mfma_f32_16x16x32_bf16 v[72:75], v[166:169], v[198:201], v[72:75]
	s_barrier
	s_add_i32 s16, 0, 0x14000
	v_add_u32_e32 v148, s16, v151
	s_add_i32 s43, s87, s17
	ds_read_b128 v[232:235], v148
	ds_read_b128 v[236:239], v148 offset:1024
	ds_read_b128 v[240:243], v148 offset:2048
	ds_read_b128 v[244:247], v148 offset:3072
	v_lshl_add_u64 v[148:149], s[34:35], 0, v[160:161]
	s_mov_b32 m0, s43
	v_lshl_add_u64 v[202:203], s[34:35], 0, v[140:141]
	global_load_lds_dwordx4 v[148:149], off
	s_add_i32 m0, s43, 0x2000
	s_nop 0
	global_load_lds_dwordx4 v[202:203], off
	s_barrier
	s_waitcnt lgkmcnt(0)
	s_waitcnt lgkmcnt(0)
	v_mfma_f32_16x16x32_bf16 v[116:119], v[232:235], v[170:173], v[116:119]
	v_mfma_f32_16x16x32_bf16 v[112:115], v[240:243], v[170:173], v[112:115]
	v_mfma_f32_16x16x32_bf16 v[100:103], v[232:235], v[178:181], v[100:103]
	v_mfma_f32_16x16x32_bf16 v[96:99], v[240:243], v[178:181], v[96:99]
	v_mfma_f32_16x16x32_bf16 v[84:87], v[232:235], v[186:189], v[84:87]
	v_mfma_f32_16x16x32_bf16 v[80:83], v[240:243], v[186:189], v[80:83]
	v_mfma_f32_16x16x32_bf16 v[68:71], v[232:235], v[194:197], v[68:71]
	v_mfma_f32_16x16x32_bf16 v[64:67], v[240:243], v[194:197], v[64:67]
	v_mfma_f32_16x16x32_bf16 v[116:119], v[236:239], v[174:177], v[116:119]
	v_mfma_f32_16x16x32_bf16 v[112:115], v[244:247], v[174:177], v[112:115]
	v_mfma_f32_16x16x32_bf16 v[100:103], v[236:239], v[182:185], v[100:103]
	v_mfma_f32_16x16x32_bf16 v[96:99], v[244:247], v[182:185], v[96:99]
	v_mfma_f32_16x16x32_bf16 v[84:87], v[236:239], v[190:193], v[84:87]
	v_mfma_f32_16x16x32_bf16 v[80:83], v[244:247], v[190:193], v[80:83]
	v_mfma_f32_16x16x32_bf16 v[68:71], v[236:239], v[198:201], v[68:71]
	v_mfma_f32_16x16x32_bf16 v[64:67], v[244:247], v[198:201], v[64:67]
	s_mov_b32 m0, s22
	v_lshl_add_u64 v[206:207], s[20:21], 0, v[136:137]
	s_barrier
	ds_read_b128 v[170:173], v154 offset:16384
	ds_read_b128 v[174:177], v154 offset:17408
	ds_read_b128 v[178:181], v154 offset:18432
	ds_read_b128 v[182:185], v154 offset:19456
	ds_read_b128 v[186:189], v154 offset:20480
	ds_read_b128 v[190:193], v154 offset:21504
	ds_read_b128 v[194:197], v154 offset:22528
	ds_read_b128 v[198:201], v154 offset:23552
	global_load_lds_dwordx4 v[206:207], off
	v_lshl_add_u64 v[210:211], s[20:21], 0, v[138:139]
	s_mov_b32 m0, s23
	s_nop 0
	global_load_lds_dwordx4 v[210:211], off
	s_barrier
	s_waitcnt lgkmcnt(0)
	s_waitcnt lgkmcnt(0)
	v_mfma_f32_16x16x32_bf16 v[60:63], v[128:131], v[170:173], v[60:63]
	v_mfma_f32_16x16x32_bf16 v[56:59], v[156:159], v[170:173], v[56:59]
	v_mfma_f32_16x16x32_bf16 v[44:47], v[128:131], v[178:181], v[44:47]
	v_mfma_f32_16x16x32_bf16 v[40:43], v[156:159], v[178:181], v[40:43]
	v_mfma_f32_16x16x32_bf16 v[28:31], v[128:131], v[186:189], v[28:31]
	v_mfma_f32_16x16x32_bf16 v[24:27], v[156:159], v[186:189], v[24:27]
	v_mfma_f32_16x16x32_bf16 v[12:15], v[128:131], v[194:197], v[12:15]
	v_mfma_f32_16x16x32_bf16 v[8:11], v[156:159], v[194:197], v[8:11]
	v_mfma_f32_16x16x32_bf16 v[60:63], v[132:135], v[174:177], v[60:63]
	v_mfma_f32_16x16x32_bf16 v[56:59], v[166:169], v[174:177], v[56:59]
	v_mfma_f32_16x16x32_bf16 v[44:47], v[132:135], v[182:185], v[44:47]
	v_mfma_f32_16x16x32_bf16 v[40:43], v[166:169], v[182:185], v[40:43]
	v_mfma_f32_16x16x32_bf16 v[28:31], v[132:135], v[190:193], v[28:31]
	v_mfma_f32_16x16x32_bf16 v[24:27], v[166:169], v[190:193], v[24:27]
	v_mfma_f32_16x16x32_bf16 v[12:15], v[132:135], v[198:201], v[12:15]
	v_mfma_f32_16x16x32_bf16 v[8:11], v[166:169], v[198:201], v[8:11]
	s_barrier
	s_add_u32 s34, s34, s64
	s_addc_u32 s35, s35, s65
	s_add_i32 s16, s16, s17
	v_lshl_add_u64 v[248:249], s[34:35], 0, v[160:161]
	s_mov_b32 m0, s16
	v_lshl_add_u64 v[250:251], s[34:35], 0, v[140:141]
	global_load_lds_dwordx4 v[248:249], off
	s_add_i32 m0, s16, 0x2000
	s_nop 0
	global_load_lds_dwordx4 v[250:251], off
	s_waitcnt vmcnt(6)
	s_barrier
	v_mfma_f32_16x16x32_bf16 v[52:55], v[232:235], v[170:173], v[52:55]
	v_mfma_f32_16x16x32_bf16 v[48:51], v[240:243], v[170:173], v[48:51]
	v_mfma_f32_16x16x32_bf16 v[36:39], v[232:235], v[178:181], v[36:39]
	v_mfma_f32_16x16x32_bf16 v[32:35], v[240:243], v[178:181], v[32:35]
	v_mfma_f32_16x16x32_bf16 v[20:23], v[232:235], v[186:189], v[20:23]
	v_mfma_f32_16x16x32_bf16 v[16:19], v[240:243], v[186:189], v[16:19]
	v_mfma_f32_16x16x32_bf16 v[4:7], v[232:235], v[194:197], v[4:7]
	v_mfma_f32_16x16x32_bf16 v[0:3], v[240:243], v[194:197], v[0:3]
	v_mfma_f32_16x16x32_bf16 v[52:55], v[236:239], v[174:177], v[52:55]
	v_mfma_f32_16x16x32_bf16 v[48:51], v[244:247], v[174:177], v[48:51]
	v_mfma_f32_16x16x32_bf16 v[36:39], v[236:239], v[182:185], v[36:39]
	v_mfma_f32_16x16x32_bf16 v[32:35], v[244:247], v[182:185], v[32:35]
	v_mfma_f32_16x16x32_bf16 v[20:23], v[236:239], v[190:193], v[20:23]
	v_mfma_f32_16x16x32_bf16 v[16:19], v[244:247], v[190:193], v[16:19]
	v_mfma_f32_16x16x32_bf16 v[4:7], v[236:239], v[198:201], v[4:7]
	v_mfma_f32_16x16x32_bf16 v[0:3], v[244:247], v[198:201], v[0:3]
	s_add_i32 s16, 0, 0x18000
	v_add_u32_e32 v155, s16, v151
	s_barrier
	ds_read_b128 v[128:131], v155
	ds_read_b128 v[132:135], v155 offset:1024
	ds_read_b128 v[156:159], v155 offset:2048
	ds_read_b128 v[166:169], v155 offset:3072
	s_add_u32 s20, s20, s64
	s_addc_u32 s21, s21, s65
	s_mov_b32 m0, s26
	v_lshl_add_u64 v[232:233], s[20:21], 0, v[136:137]
	ds_read_b128 v[170:173], v154 offset:32768
	ds_read_b128 v[174:177], v154 offset:33792
	ds_read_b128 v[178:181], v154 offset:34816
	ds_read_b128 v[182:185], v154 offset:35840
	ds_read_b128 v[186:189], v154 offset:36864
	ds_read_b128 v[190:193], v154 offset:37888
	ds_read_b128 v[194:197], v154 offset:38912
	ds_read_b128 v[198:201], v154 offset:39936
	global_load_lds_dwordx4 v[232:233], off
	v_lshl_add_u64 v[232:233], s[20:21], 0, v[138:139]
	s_mov_b32 m0, s27
	s_nop 0
	global_load_lds_dwordx4 v[232:233], off
	s_waitcnt lgkmcnt(8)
	s_barrier
	s_waitcnt lgkmcnt(0)
	s_waitcnt lgkmcnt(0)
	v_mfma_f32_16x16x32_bf16 v[124:127], v[128:131], v[170:173], v[124:127]
	v_mfma_f32_16x16x32_bf16 v[120:123], v[156:159], v[170:173], v[120:123]
	v_mfma_f32_16x16x32_bf16 v[108:111], v[128:131], v[178:181], v[108:111]
	v_mfma_f32_16x16x32_bf16 v[104:107], v[156:159], v[178:181], v[104:107]
	v_mfma_f32_16x16x32_bf16 v[92:95], v[128:131], v[186:189], v[92:95]
	v_mfma_f32_16x16x32_bf16 v[88:91], v[156:159], v[186:189], v[88:91]
	v_mfma_f32_16x16x32_bf16 v[76:79], v[128:131], v[194:197], v[76:79]
	v_mfma_f32_16x16x32_bf16 v[72:75], v[156:159], v[194:197], v[72:75]
	v_mfma_f32_16x16x32_bf16 v[124:127], v[132:135], v[174:177], v[124:127]
	v_mfma_f32_16x16x32_bf16 v[120:123], v[166:169], v[174:177], v[120:123]
	v_mfma_f32_16x16x32_bf16 v[108:111], v[132:135], v[182:185], v[108:111]
	v_mfma_f32_16x16x32_bf16 v[104:107], v[166:169], v[182:185], v[104:107]
	v_mfma_f32_16x16x32_bf16 v[92:95], v[132:135], v[190:193], v[92:95]
	v_mfma_f32_16x16x32_bf16 v[88:91], v[166:169], v[190:193], v[88:91]
	v_mfma_f32_16x16x32_bf16 v[76:79], v[132:135], v[198:201], v[76:79]
	v_mfma_f32_16x16x32_bf16 v[72:75], v[166:169], v[198:201], v[72:75]
	s_barrier
	s_add_i32 s20, 0, 0x1c000
	s_add_i32 s16, s16, s17
	v_add_u32_e32 v155, s20, v151
	v_lshl_add_u64 v[148:149], v[148:149], 0, s[96:97]
	s_mov_b32 m0, s16
	ds_read_b128 v[232:235], v155
	ds_read_b128 v[236:239], v155 offset:1024
	ds_read_b128 v[240:243], v155 offset:2048
	ds_read_b128 v[244:247], v155 offset:3072
	global_load_lds_dwordx4 v[148:149], off
	v_lshl_add_u64 v[148:149], v[202:203], 0, s[96:97]
	s_add_i32 m0, s16, 0x2000
	s_nop 0
	global_load_lds_dwordx4 v[148:149], off
	s_barrier
	s_waitcnt lgkmcnt(0)
	s_waitcnt lgkmcnt(0)
	v_mfma_f32_16x16x32_bf16 v[116:119], v[232:235], v[170:173], v[116:119]
	v_mfma_f32_16x16x32_bf16 v[112:115], v[240:243], v[170:173], v[112:115]
	v_mfma_f32_16x16x32_bf16 v[100:103], v[232:235], v[178:181], v[100:103]
	v_mfma_f32_16x16x32_bf16 v[96:99], v[240:243], v[178:181], v[96:99]
	v_mfma_f32_16x16x32_bf16 v[84:87], v[232:235], v[186:189], v[84:87]
	v_mfma_f32_16x16x32_bf16 v[80:83], v[240:243], v[186:189], v[80:83]
	v_mfma_f32_16x16x32_bf16 v[68:71], v[232:235], v[194:197], v[68:71]
	v_mfma_f32_16x16x32_bf16 v[64:67], v[240:243], v[194:197], v[64:67]
	v_mfma_f32_16x16x32_bf16 v[116:119], v[236:239], v[174:177], v[116:119]
	v_mfma_f32_16x16x32_bf16 v[112:115], v[244:247], v[174:177], v[112:115]
	v_mfma_f32_16x16x32_bf16 v[100:103], v[236:239], v[182:185], v[100:103]
	v_mfma_f32_16x16x32_bf16 v[96:99], v[244:247], v[182:185], v[96:99]
	v_mfma_f32_16x16x32_bf16 v[84:87], v[236:239], v[190:193], v[84:87]
	v_mfma_f32_16x16x32_bf16 v[80:83], v[244:247], v[190:193], v[80:83]
	v_mfma_f32_16x16x32_bf16 v[68:71], v[236:239], v[198:201], v[68:71]
	v_mfma_f32_16x16x32_bf16 v[64:67], v[244:247], v[198:201], v[64:67]
	s_mov_b32 m0, s28
	v_lshl_add_u64 v[148:149], v[206:207], 0, s[96:97]
	s_barrier
	ds_read_b128 v[170:173], v154 offset:49152
	ds_read_b128 v[174:177], v154 offset:50176
	ds_read_b128 v[178:181], v154 offset:51200
	ds_read_b128 v[182:185], v154 offset:52224
	ds_read_b128 v[186:189], v154 offset:53248
	ds_read_b128 v[190:193], v154 offset:54272
	ds_read_b128 v[194:197], v154 offset:55296
	ds_read_b128 v[198:201], v154 offset:56320
	global_load_lds_dwordx4 v[148:149], off
	v_lshl_add_u64 v[148:149], v[210:211], 0, s[96:97]
	s_mov_b32 m0, s29
	s_nop 0
	global_load_lds_dwordx4 v[148:149], off
	s_barrier
	s_waitcnt lgkmcnt(0)
	s_waitcnt lgkmcnt(0)
	v_mfma_f32_16x16x32_bf16 v[60:63], v[128:131], v[170:173], v[60:63]
	v_mfma_f32_16x16x32_bf16 v[56:59], v[156:159], v[170:173], v[56:59]
	v_mfma_f32_16x16x32_bf16 v[44:47], v[128:131], v[178:181], v[44:47]
	v_mfma_f32_16x16x32_bf16 v[40:43], v[156:159], v[178:181], v[40:43]
	v_mfma_f32_16x16x32_bf16 v[28:31], v[128:131], v[186:189], v[28:31]
	v_mfma_f32_16x16x32_bf16 v[24:27], v[156:159], v[186:189], v[24:27]
	v_mfma_f32_16x16x32_bf16 v[12:15], v[128:131], v[194:197], v[12:15]
	v_mfma_f32_16x16x32_bf16 v[8:11], v[156:159], v[194:197], v[8:11]
	v_mfma_f32_16x16x32_bf16 v[60:63], v[132:135], v[174:177], v[60:63]
	v_mfma_f32_16x16x32_bf16 v[56:59], v[166:169], v[174:177], v[56:59]
	v_mfma_f32_16x16x32_bf16 v[44:47], v[132:135], v[182:185], v[44:47]
	v_mfma_f32_16x16x32_bf16 v[40:43], v[166:169], v[182:185], v[40:43]
	v_mfma_f32_16x16x32_bf16 v[28:31], v[132:135], v[190:193], v[28:31]
	v_mfma_f32_16x16x32_bf16 v[24:27], v[166:169], v[190:193], v[24:27]
	v_mfma_f32_16x16x32_bf16 v[12:15], v[132:135], v[198:201], v[12:15]
	v_mfma_f32_16x16x32_bf16 v[8:11], v[166:169], v[198:201], v[8:11]
	s_barrier
	s_add_i32 s16, s20, s17
	v_lshl_add_u64 v[128:129], v[248:249], 0, s[96:97]
	s_mov_b32 m0, s16
	s_nop 0
	global_load_lds_dwordx4 v[128:129], off
	v_lshl_add_u64 v[128:129], v[250:251], 0, s[96:97]
	s_add_i32 m0, s16, 0x2000
	s_nop 0
	global_load_lds_dwordx4 v[128:129], off
	s_waitcnt vmcnt(6)
	s_barrier
	v_mfma_f32_16x16x32_bf16 v[52:55], v[232:235], v[170:173], v[52:55]
	v_mfma_f32_16x16x32_bf16 v[48:51], v[240:243], v[170:173], v[48:51]
	v_mfma_f32_16x16x32_bf16 v[36:39], v[232:235], v[178:181], v[36:39]
	v_mfma_f32_16x16x32_bf16 v[32:35], v[240:243], v[178:181], v[32:35]
	v_mfma_f32_16x16x32_bf16 v[20:23], v[232:235], v[186:189], v[20:23]
	v_mfma_f32_16x16x32_bf16 v[16:19], v[240:243], v[186:189], v[16:19]
	v_mfma_f32_16x16x32_bf16 v[4:7], v[232:235], v[194:197], v[4:7]
	v_mfma_f32_16x16x32_bf16 v[0:3], v[240:243], v[194:197], v[0:3]
	v_mfma_f32_16x16x32_bf16 v[52:55], v[236:239], v[174:177], v[52:55]
	v_mfma_f32_16x16x32_bf16 v[48:51], v[244:247], v[174:177], v[48:51]
	v_mfma_f32_16x16x32_bf16 v[36:39], v[236:239], v[182:185], v[36:39]
	v_mfma_f32_16x16x32_bf16 v[32:35], v[244:247], v[182:185], v[32:35]
	v_mfma_f32_16x16x32_bf16 v[20:23], v[236:239], v[190:193], v[20:23]
	v_mfma_f32_16x16x32_bf16 v[16:19], v[244:247], v[190:193], v[16:19]
	v_mfma_f32_16x16x32_bf16 v[4:7], v[236:239], v[198:201], v[4:7]
	v_mfma_f32_16x16x32_bf16 v[0:3], v[244:247], v[198:201], v[0:3]
	s_add_u32 s38, s38, 0x100
	s_addc_u32 s39, s39, 0
	s_add_u32 vcc_lo, vcc_lo, 0x100
	s_addc_u32 vcc_hi, vcc_hi, 0
	s_cmp_ge_i32 s42, s41
	s_mov_b32 s20, s42
	s_barrier
	s_cbranch_scc0 .LBB0_348
	v_readlane_b32 s20, v254, 5
	v_mov_b32 v128, s20
	v_readlane_b32 s21, v254, 6
	v_readfirstlane_b32 s16, v128
	v_mov_b32 v128, s21
	s_add_u32 s34, s16, 0xc400000
	v_readfirstlane_b32 s52, v128
	s_addc_u32 s35, s52, 0
	s_mov_b64 s[44:45], -1
	s_mov_b64 s[20:21], 0
	s_cmp_lt_i32 s2, 5
	s_mov_b64 s[38:39], 0
	s_mov_b64 s[42:43], 0
	s_cbranch_scc1 .LBB0_353
	s_mov_b64 s[42:43], -1
	s_mov_b64 s[44:45], 0
	s_cmp_gt_i32 s2, 5
	s_cbranch_scc0 .LBB0_353
	s_cmp_gt_i32 s2, 6
	s_cbranch_scc0 .LBB0_371
	s_cmp_eq_u32 s2, 7
	s_cselect_b64 s[42:43], -1, 0

.LBB0_408:
	s_add_u32 s17, s12, 0x100
	s_addc_u32 s20, s13, 0
	s_add_u32 s8, s14, 0x80
	v_mov_b64_e32 v[0:1], 0
	v_mov_b64_e32 v[2:3], 0
	v_mov_b64_e32 v[4:5], 0
	v_mov_b64_e32 v[6:7], 0
	v_mov_b64_e32 v[8:9], 0
	v_mov_b64_e32 v[10:11], 0
	v_mov_b64_e32 v[12:13], 0
	v_mov_b64_e32 v[14:15], 0
	v_mov_b64_e32 v[16:17], 0
	v_mov_b64_e32 v[18:19], 0
	v_mov_b64_e32 v[20:21], 0
	v_mov_b64_e32 v[22:23], 0
	v_mov_b64_e32 v[24:25], 0
	v_mov_b64_e32 v[26:27], 0
	v_mov_b64_e32 v[28:29], 0
	v_mov_b64_e32 v[30:31], 0
	v_mov_b64_e32 v[32:33], 0
	v_mov_b64_e32 v[34:35], 0
	v_mov_b64_e32 v[36:37], 0
	v_mov_b64_e32 v[38:39], 0
	v_mov_b64_e32 v[40:41], 0
	v_mov_b64_e32 v[42:43], 0
	v_mov_b64_e32 v[44:45], 0
	v_mov_b64_e32 v[46:47], 0
	v_mov_b64_e32 v[48:49], 0
	v_mov_b64_e32 v[50:51], 0
	v_mov_b64_e32 v[52:53], 0
	v_mov_b64_e32 v[54:55], 0
	v_mov_b64_e32 v[56:57], 0
	v_mov_b64_e32 v[58:59], 0
	v_mov_b64_e32 v[60:61], 0
	v_mov_b64_e32 v[62:63], 0
	v_mov_b64_e32 v[64:65], 0
	v_mov_b64_e32 v[66:67], 0
	v_mov_b64_e32 v[68:69], 0
	v_mov_b64_e32 v[70:71], 0
	v_mov_b64_e32 v[72:73], 0
	v_mov_b64_e32 v[74:75], 0
	v_mov_b64_e32 v[76:77], 0
	v_mov_b64_e32 v[78:79], 0
	v_mov_b64_e32 v[80:81], 0
	v_mov_b64_e32 v[82:83], 0
	v_mov_b64_e32 v[84:85], 0
	v_mov_b64_e32 v[86:87], 0
	v_mov_b64_e32 v[88:89], 0
	v_mov_b64_e32 v[90:91], 0
	v_mov_b64_e32 v[92:93], 0
	v_mov_b64_e32 v[94:95], 0
	v_mov_b64_e32 v[96:97], 0
	v_mov_b64_e32 v[98:99], 0
	v_mov_b64_e32 v[100:101], 0
	v_mov_b64_e32 v[102:103], 0
	v_mov_b64_e32 v[104:105], 0
	v_mov_b64_e32 v[106:107], 0
	v_mov_b64_e32 v[108:109], 0
	v_mov_b64_e32 v[110:111], 0
	v_mov_b64_e32 v[112:113], 0
	v_mov_b64_e32 v[114:115], 0
	v_mov_b64_e32 v[116:117], 0
	v_mov_b64_e32 v[118:119], 0
	v_mov_b64_e32 v[120:121], 0
	v_mov_b64_e32 v[122:123], 0
	v_mov_b64_e32 v[124:125], 0
	v_mov_b64_e32 v[126:127], 0
	s_addc_u32 s9, s15, 0
	s_mov_b32 s10, 0
	s_waitcnt vmcnt(0)
.LBB0_409:
	v_add_u32_e32 v140, s87, v233
	ds_read_b128 v[128:131], v140
	ds_read_b128 v[132:135], v140 offset:1024
	ds_read_b128 v[136:139], v140 offset:2048
	ds_read_b128 v[140:143], v140 offset:3072
	s_add_i32 s14, s10, 2
	s_add_u32 s12, s8, 0x80
	s_addc_u32 s11, s9, 0
	s_cmp_eq_u32 s44, s10
	s_cselect_b32 s10, s72, s12
	s_cselect_b32 s11, s73, s11
	s_cselect_b32 s13, s77, s20
	s_cselect_b32 s12, s76, s17
	v_lshl_add_u64 v[192:193], s[8:9], 0, v[174:175]
	s_add_i32 m0, s34, 0xc000
	ds_read_b128 v[144:147], v235
	ds_read_b128 v[148:151], v235 offset:1024
	ds_read_b128 v[152:155], v235 offset:2048
	ds_read_b128 v[156:159], v235 offset:3072
	ds_read_b128 v[176:179], v235 offset:4096
	ds_read_b128 v[180:183], v235 offset:5120
	ds_read_b128 v[184:187], v235 offset:6144
	ds_read_b128 v[188:191], v235 offset:7168
	global_load_lds_dwordx4 v[192:193], off
	v_lshl_add_u64 v[192:193], s[8:9], 0, v[172:173]
	s_add_i32 m0, s34, 0xe000
	s_nop 0
	global_load_lds_dwordx4 v[192:193], off
	s_waitcnt lgkmcnt(8)
	s_barrier
	s_waitcnt lgkmcnt(0)
	s_waitcnt lgkmcnt(0)
	v_mfma_f32_16x16x32_bf16 v[124:127], v[128:131], v[144:147], v[124:127]
	v_mfma_f32_16x16x32_bf16 v[120:123], v[136:139], v[144:147], v[120:123]
	v_mfma_f32_16x16x32_bf16 v[108:111], v[128:131], v[152:155], v[108:111]
	v_mfma_f32_16x16x32_bf16 v[104:107], v[136:139], v[152:155], v[104:107]
	v_mfma_f32_16x16x32_bf16 v[92:95], v[128:131], v[176:179], v[92:95]
	v_mfma_f32_16x16x32_bf16 v[88:91], v[136:139], v[176:179], v[88:91]
	v_mfma_f32_16x16x32_bf16 v[76:79], v[128:131], v[184:187], v[76:79]
	v_mfma_f32_16x16x32_bf16 v[72:75], v[136:139], v[184:187], v[72:75]
	v_mfma_f32_16x16x32_bf16 v[124:127], v[132:135], v[148:151], v[124:127]
	v_mfma_f32_16x16x32_bf16 v[120:123], v[140:143], v[148:151], v[120:123]
	v_mfma_f32_16x16x32_bf16 v[108:111], v[132:135], v[156:159], v[108:111]
	v_mfma_f32_16x16x32_bf16 v[104:107], v[140:143], v[156:159], v[104:107]
	v_mfma_f32_16x16x32_bf16 v[92:95], v[132:135], v[180:183], v[92:95]
	v_mfma_f32_16x16x32_bf16 v[88:91], v[140:143], v[180:183], v[88:91]
	v_mfma_f32_16x16x32_bf16 v[76:79], v[132:135], v[188:191], v[76:79]
	v_mfma_f32_16x16x32_bf16 v[72:75], v[140:143], v[188:191], v[72:75]
	s_barrier
	s_add_i32 s15, 0, 0x14000
	v_add_u32_e32 v206, s15, v233
	s_add_i32 s21, s87, s31
	ds_read_b128 v[192:195], v206
	ds_read_b128 v[196:199], v206 offset:1024
	ds_read_b128 v[200:203], v206 offset:2048
	ds_read_b128 v[236:239], v206 offset:3072
	v_lshl_add_u64 v[206:207], s[12:13], 0, v[160:161]
	s_mov_b32 m0, s21
	v_lshl_add_u64 v[210:211], s[12:13], 0, v[170:171]
	global_load_lds_dwordx4 v[206:207], off
	s_add_i32 m0, s21, 0x2000
	s_nop 0
	global_load_lds_dwordx4 v[210:211], off
	s_barrier
	s_waitcnt lgkmcnt(0)
	s_waitcnt lgkmcnt(0)
	v_mfma_f32_16x16x32_bf16 v[116:119], v[192:195], v[144:147], v[116:119]
	v_mfma_f32_16x16x32_bf16 v[112:115], v[200:203], v[144:147], v[112:115]
	v_mfma_f32_16x16x32_bf16 v[100:103], v[192:195], v[152:155], v[100:103]
	v_mfma_f32_16x16x32_bf16 v[96:99], v[200:203], v[152:155], v[96:99]
	v_mfma_f32_16x16x32_bf16 v[84:87], v[192:195], v[176:179], v[84:87]
	v_mfma_f32_16x16x32_bf16 v[80:83], v[200:203], v[176:179], v[80:83]
	v_mfma_f32_16x16x32_bf16 v[68:71], v[192:195], v[184:187], v[68:71]
	v_mfma_f32_16x16x32_bf16 v[64:67], v[200:203], v[184:187], v[64:67]
	v_mfma_f32_16x16x32_bf16 v[116:119], v[196:199], v[148:151], v[116:119]
	v_mfma_f32_16x16x32_bf16 v[112:115], v[236:239], v[148:151], v[112:115]
	v_mfma_f32_16x16x32_bf16 v[100:103], v[196:199], v[156:159], v[100:103]
	v_mfma_f32_16x16x32_bf16 v[96:99], v[236:239], v[156:159], v[96:99]
	v_mfma_f32_16x16x32_bf16 v[84:87], v[196:199], v[180:183], v[84:87]
	v_mfma_f32_16x16x32_bf16 v[80:83], v[236:239], v[180:183], v[80:83]
	v_mfma_f32_16x16x32_bf16 v[68:71], v[196:199], v[188:191], v[68:71]
	v_mfma_f32_16x16x32_bf16 v[64:67], v[236:239], v[188:191], v[64:67]
	s_mov_b32 m0, s34
	v_lshl_add_u64 v[240:241], s[10:11], 0, v[166:167]
	s_barrier
	ds_read_b128 v[144:147], v235 offset:16384
	ds_read_b128 v[148:151], v235 offset:17408
	ds_read_b128 v[152:155], v235 offset:18432
	ds_read_b128 v[156:159], v235 offset:19456
	ds_read_b128 v[176:179], v235 offset:20480
	ds_read_b128 v[180:183], v235 offset:21504
	ds_read_b128 v[184:187], v235 offset:22528
	ds_read_b128 v[188:191], v235 offset:23552
	global_load_lds_dwordx4 v[240:241], off
	v_lshl_add_u64 v[242:243], s[10:11], 0, v[168:169]
	s_mov_b32 m0, s35
	s_nop 0
	global_load_lds_dwordx4 v[242:243], off
	s_barrier
	s_waitcnt lgkmcnt(0)
	s_waitcnt lgkmcnt(0)
	v_mfma_f32_16x16x32_bf16 v[60:63], v[128:131], v[144:147], v[60:63]
	v_mfma_f32_16x16x32_bf16 v[56:59], v[136:139], v[144:147], v[56:59]
	v_mfma_f32_16x16x32_bf16 v[44:47], v[128:131], v[152:155], v[44:47]
	v_mfma_f32_16x16x32_bf16 v[40:43], v[136:139], v[152:155], v[40:43]
	v_mfma_f32_16x16x32_bf16 v[28:31], v[128:131], v[176:179], v[28:31]
	v_mfma_f32_16x16x32_bf16 v[24:27], v[136:139], v[176:179], v[24:27]
	v_mfma_f32_16x16x32_bf16 v[12:15], v[128:131], v[184:187], v[12:15]
	v_mfma_f32_16x16x32_bf16 v[8:11], v[136:139], v[184:187], v[8:11]
	v_mfma_f32_16x16x32_bf16 v[60:63], v[132:135], v[148:151], v[60:63]
	v_mfma_f32_16x16x32_bf16 v[56:59], v[140:143], v[148:151], v[56:59]
	v_mfma_f32_16x16x32_bf16 v[44:47], v[132:135], v[156:159], v[44:47]
	v_mfma_f32_16x16x32_bf16 v[40:43], v[140:143], v[156:159], v[40:43]
	v_mfma_f32_16x16x32_bf16 v[28:31], v[132:135], v[180:183], v[28:31]
	v_mfma_f32_16x16x32_bf16 v[24:27], v[140:143], v[180:183], v[24:27]
	v_mfma_f32_16x16x32_bf16 v[12:15], v[132:135], v[188:191], v[12:15]
	v_mfma_f32_16x16x32_bf16 v[8:11], v[140:143], v[188:191], v[8:11]
	s_barrier
	s_add_u32 s12, s12, s64
	s_addc_u32 s13, s13, s65
	s_add_i32 s15, s15, s31
	v_lshl_add_u64 v[244:245], s[12:13], 0, v[160:161]
	s_mov_b32 m0, s15
	v_lshl_add_u64 v[246:247], s[12:13], 0, v[170:171]
	global_load_lds_dwordx4 v[244:245], off
	s_add_i32 m0, s15, 0x2000
	s_nop 0
	global_load_lds_dwordx4 v[246:247], off
	s_waitcnt vmcnt(6)
	s_barrier
	v_mfma_f32_16x16x32_bf16 v[52:55], v[192:195], v[144:147], v[52:55]
	v_mfma_f32_16x16x32_bf16 v[48:51], v[200:203], v[144:147], v[48:51]
	v_mfma_f32_16x16x32_bf16 v[36:39], v[192:195], v[152:155], v[36:39]
	v_mfma_f32_16x16x32_bf16 v[32:35], v[200:203], v[152:155], v[32:35]
	v_mfma_f32_16x16x32_bf16 v[20:23], v[192:195], v[176:179], v[20:23]
	v_mfma_f32_16x16x32_bf16 v[16:19], v[200:203], v[176:179], v[16:19]
	v_mfma_f32_16x16x32_bf16 v[4:7], v[192:195], v[184:187], v[4:7]
	v_mfma_f32_16x16x32_bf16 v[0:3], v[200:203], v[184:187], v[0:3]
	v_mfma_f32_16x16x32_bf16 v[52:55], v[196:199], v[148:151], v[52:55]
	v_mfma_f32_16x16x32_bf16 v[48:51], v[236:239], v[148:151], v[48:51]
	v_mfma_f32_16x16x32_bf16 v[36:39], v[196:199], v[156:159], v[36:39]
	v_mfma_f32_16x16x32_bf16 v[32:35], v[236:239], v[156:159], v[32:35]
	v_mfma_f32_16x16x32_bf16 v[20:23], v[196:199], v[180:183], v[20:23]
	v_mfma_f32_16x16x32_bf16 v[16:19], v[236:239], v[180:183], v[16:19]
	v_mfma_f32_16x16x32_bf16 v[4:7], v[196:199], v[188:191], v[4:7]
	v_mfma_f32_16x16x32_bf16 v[0:3], v[236:239], v[188:191], v[0:3]
	s_add_i32 s12, 0, 0x18000
	v_add_u32_e32 v140, s12, v233
	s_barrier
	ds_read_b128 v[128:131], v140
	ds_read_b128 v[132:135], v140 offset:1024
	ds_read_b128 v[136:139], v140 offset:2048
	ds_read_b128 v[140:143], v140 offset:3072
	s_add_u32 s10, s10, s64
	s_addc_u32 s11, s11, s65
	s_mov_b32 m0, s38
	v_lshl_add_u64 v[192:193], s[10:11], 0, v[166:167]
	ds_read_b128 v[144:147], v235 offset:32768
	ds_read_b128 v[148:151], v235 offset:33792
	ds_read_b128 v[152:155], v235 offset:34816
	ds_read_b128 v[156:159], v235 offset:35840
	ds_read_b128 v[176:179], v235 offset:36864
	ds_read_b128 v[180:183], v235 offset:37888
	ds_read_b128 v[184:187], v235 offset:38912
	ds_read_b128 v[188:191], v235 offset:39936
	global_load_lds_dwordx4 v[192:193], off
	v_lshl_add_u64 v[192:193], s[10:11], 0, v[168:169]
	s_mov_b32 m0, s39
	s_nop 0
	global_load_lds_dwordx4 v[192:193], off
	s_waitcnt lgkmcnt(8)
	s_barrier
	s_waitcnt lgkmcnt(0)
	s_waitcnt lgkmcnt(0)
	v_mfma_f32_16x16x32_bf16 v[124:127], v[128:131], v[144:147], v[124:127]
	v_mfma_f32_16x16x32_bf16 v[120:123], v[136:139], v[144:147], v[120:123]
	v_mfma_f32_16x16x32_bf16 v[108:111], v[128:131], v[152:155], v[108:111]
	v_mfma_f32_16x16x32_bf16 v[104:107], v[136:139], v[152:155], v[104:107]
	v_mfma_f32_16x16x32_bf16 v[92:95], v[128:131], v[176:179], v[92:95]
	v_mfma_f32_16x16x32_bf16 v[88:91], v[136:139], v[176:179], v[88:91]
	v_mfma_f32_16x16x32_bf16 v[76:79], v[128:131], v[184:187], v[76:79]
	v_mfma_f32_16x16x32_bf16 v[72:75], v[136:139], v[184:187], v[72:75]
	v_mfma_f32_16x16x32_bf16 v[124:127], v[132:135], v[148:151], v[124:127]
	v_mfma_f32_16x16x32_bf16 v[120:123], v[140:143], v[148:151], v[120:123]
	v_mfma_f32_16x16x32_bf16 v[108:111], v[132:135], v[156:159], v[108:111]
	v_mfma_f32_16x16x32_bf16 v[104:107], v[140:143], v[156:159], v[104:107]
	v_mfma_f32_16x16x32_bf16 v[92:95], v[132:135], v[180:183], v[92:95]
	v_mfma_f32_16x16x32_bf16 v[88:91], v[140:143], v[180:183], v[88:91]
	v_mfma_f32_16x16x32_bf16 v[76:79], v[132:135], v[188:191], v[76:79]
	v_mfma_f32_16x16x32_bf16 v[72:75], v[140:143], v[188:191], v[72:75]
	s_barrier
	s_add_i32 s10, 0, 0x1c000
	s_add_i32 s11, s12, s31
	v_add_u32_e32 v236, s10, v233
	v_lshl_add_u64 v[206:207], v[206:207], 0, s[96:97]
	s_mov_b32 m0, s11
	ds_read_b128 v[192:195], v236
	ds_read_b128 v[196:199], v236 offset:1024
	ds_read_b128 v[200:203], v236 offset:2048
	ds_read_b128 v[236:239], v236 offset:3072
	global_load_lds_dwordx4 v[206:207], off
	v_lshl_add_u64 v[206:207], v[210:211], 0, s[96:97]
	s_add_i32 m0, s11, 0x2000
	s_nop 0
	global_load_lds_dwordx4 v[206:207], off
	s_barrier
	s_waitcnt lgkmcnt(0)
	s_waitcnt lgkmcnt(0)
	v_mfma_f32_16x16x32_bf16 v[116:119], v[192:195], v[144:147], v[116:119]
	v_mfma_f32_16x16x32_bf16 v[112:115], v[200:203], v[144:147], v[112:115]
	v_mfma_f32_16x16x32_bf16 v[100:103], v[192:195], v[152:155], v[100:103]
	v_mfma_f32_16x16x32_bf16 v[96:99], v[200:203], v[152:155], v[96:99]
	v_mfma_f32_16x16x32_bf16 v[84:87], v[192:195], v[176:179], v[84:87]
	v_mfma_f32_16x16x32_bf16 v[80:83], v[200:203], v[176:179], v[80:83]
	v_mfma_f32_16x16x32_bf16 v[68:71], v[192:195], v[184:187], v[68:71]
	v_mfma_f32_16x16x32_bf16 v[64:67], v[200:203], v[184:187], v[64:67]
	v_mfma_f32_16x16x32_bf16 v[116:119], v[196:199], v[148:151], v[116:119]
	v_mfma_f32_16x16x32_bf16 v[112:115], v[236:239], v[148:151], v[112:115]
	v_mfma_f32_16x16x32_bf16 v[100:103], v[196:199], v[156:159], v[100:103]
	v_mfma_f32_16x16x32_bf16 v[96:99], v[236:239], v[156:159], v[96:99]
	v_mfma_f32_16x16x32_bf16 v[84:87], v[196:199], v[180:183], v[84:87]
	v_mfma_f32_16x16x32_bf16 v[80:83], v[236:239], v[180:183], v[80:83]
	v_mfma_f32_16x16x32_bf16 v[68:71], v[196:199], v[188:191], v[68:71]
	v_mfma_f32_16x16x32_bf16 v[64:67], v[236:239], v[188:191], v[64:67]
	s_mov_b32 m0, s42
	v_lshl_add_u64 v[206:207], v[240:241], 0, s[96:97]
	s_barrier
	ds_read_b128 v[144:147], v235 offset:49152
	ds_read_b128 v[148:151], v235 offset:50176
	ds_read_b128 v[152:155], v235 offset:51200
	ds_read_b128 v[156:159], v235 offset:52224
	ds_read_b128 v[176:179], v235 offset:53248
	ds_read_b128 v[180:183], v235 offset:54272
	ds_read_b128 v[184:187], v235 offset:55296
	ds_read_b128 v[188:191], v235 offset:56320
	global_load_lds_dwordx4 v[206:207], off
	v_lshl_add_u64 v[206:207], v[242:243], 0, s[96:97]
	s_mov_b32 m0, s43
	s_nop 0
	global_load_lds_dwordx4 v[206:207], off
	s_barrier
	s_waitcnt lgkmcnt(0)
	s_waitcnt lgkmcnt(0)
	v_mfma_f32_16x16x32_bf16 v[60:63], v[128:131], v[144:147], v[60:63]
	v_mfma_f32_16x16x32_bf16 v[56:59], v[136:139], v[144:147], v[56:59]
	v_mfma_f32_16x16x32_bf16 v[44:47], v[128:131], v[152:155], v[44:47]
	v_mfma_f32_16x16x32_bf16 v[40:43], v[136:139], v[152:155], v[40:43]
	v_mfma_f32_16x16x32_bf16 v[28:31], v[128:131], v[176:179], v[28:31]
	v_mfma_f32_16x16x32_bf16 v[24:27], v[136:139], v[176:179], v[24:27]
	v_mfma_f32_16x16x32_bf16 v[12:15], v[128:131], v[184:187], v[12:15]
	v_mfma_f32_16x16x32_bf16 v[8:11], v[136:139], v[184:187], v[8:11]
	v_mfma_f32_16x16x32_bf16 v[60:63], v[132:135], v[148:151], v[60:63]
	v_mfma_f32_16x16x32_bf16 v[56:59], v[140:143], v[148:151], v[56:59]
	v_mfma_f32_16x16x32_bf16 v[44:47], v[132:135], v[156:159], v[44:47]
	v_mfma_f32_16x16x32_bf16 v[40:43], v[140:143], v[156:159], v[40:43]
	v_mfma_f32_16x16x32_bf16 v[28:31], v[132:135], v[180:183], v[28:31]
	v_mfma_f32_16x16x32_bf16 v[24:27], v[140:143], v[180:183], v[24:27]
	v_mfma_f32_16x16x32_bf16 v[12:15], v[132:135], v[188:191], v[12:15]
	v_mfma_f32_16x16x32_bf16 v[8:11], v[140:143], v[188:191], v[8:11]
	s_barrier
	s_add_i32 s10, s10, s31
	v_lshl_add_u64 v[128:129], v[244:245], 0, s[96:97]
	s_mov_b32 m0, s10
	s_nop 0
	global_load_lds_dwordx4 v[128:129], off
	v_lshl_add_u64 v[128:129], v[246:247], 0, s[96:97]
	s_add_i32 m0, s10, 0x2000
	s_nop 0
	global_load_lds_dwordx4 v[128:129], off
	s_waitcnt vmcnt(6)
	s_barrier
	v_mfma_f32_16x16x32_bf16 v[52:55], v[192:195], v[144:147], v[52:55]
	v_mfma_f32_16x16x32_bf16 v[48:51], v[200:203], v[144:147], v[48:51]
	v_mfma_f32_16x16x32_bf16 v[36:39], v[192:195], v[152:155], v[36:39]
	v_mfma_f32_16x16x32_bf16 v[32:35], v[200:203], v[152:155], v[32:35]
	v_mfma_f32_16x16x32_bf16 v[20:23], v[192:195], v[176:179], v[20:23]
	v_mfma_f32_16x16x32_bf16 v[16:19], v[200:203], v[176:179], v[16:19]
	v_mfma_f32_16x16x32_bf16 v[4:7], v[192:195], v[184:187], v[4:7]
	v_mfma_f32_16x16x32_bf16 v[0:3], v[200:203], v[184:187], v[0:3]
	v_mfma_f32_16x16x32_bf16 v[52:55], v[196:199], v[148:151], v[52:55]
	v_mfma_f32_16x16x32_bf16 v[48:51], v[236:239], v[148:151], v[48:51]
	v_mfma_f32_16x16x32_bf16 v[36:39], v[196:199], v[156:159], v[36:39]
	v_mfma_f32_16x16x32_bf16 v[32:35], v[236:239], v[156:159], v[32:35]
	v_mfma_f32_16x16x32_bf16 v[20:23], v[196:199], v[180:183], v[20:23]
	v_mfma_f32_16x16x32_bf16 v[16:19], v[236:239], v[180:183], v[16:19]
	v_mfma_f32_16x16x32_bf16 v[4:7], v[196:199], v[188:191], v[4:7]
	v_mfma_f32_16x16x32_bf16 v[0:3], v[236:239], v[188:191], v[0:3]
	s_add_u32 s17, s17, 0x100
	s_addc_u32 s20, s20, 0
	s_add_u32 s8, s8, 0x100
	s_addc_u32 s9, s9, 0
	s_cmp_ge_i32 s14, s41
	s_mov_b32 s10, s14
	s_barrier
	s_cbranch_scc0 .LBB0_409
	v_readlane_b32 s8, v254, 5
	v_mov_b32 v128, s8
	v_readlane_b32 s9, v254, 6
	v_readfirstlane_b32 s12, v128
	v_mov_b32 v128, s9
	s_cmp_lt_i32 s2, 5
	v_readfirstlane_b32 s13, v128
	s_cbranch_scc1 .LBB0_413
	s_cmp_gt_i32 s2, 6
	s_cbranch_scc0 .LBB0_414
	s_cmp_eq_u32 s2, 7
	s_cselect_b64 s[8:9], -1, 0
	s_cbranch_execz .LBB0_415
	s_branch .LBB0_416

.LBB0_616:
	s_add_u32 s17, s20, 0x100
	s_addc_u32 s24, s21, 0
	s_add_u32 s30, s30, 0x80
	v_mov_b64_e32 v[0:1], 0
	v_mov_b64_e32 v[2:3], 0
	v_mov_b64_e32 v[4:5], 0
	v_mov_b64_e32 v[6:7], 0
	v_mov_b64_e32 v[8:9], 0
	v_mov_b64_e32 v[10:11], 0
	v_mov_b64_e32 v[12:13], 0
	v_mov_b64_e32 v[14:15], 0
	v_mov_b64_e32 v[16:17], 0
	v_mov_b64_e32 v[18:19], 0
	v_mov_b64_e32 v[20:21], 0
	v_mov_b64_e32 v[22:23], 0
	v_mov_b64_e32 v[24:25], 0
	v_mov_b64_e32 v[26:27], 0
	v_mov_b64_e32 v[28:29], 0
	v_mov_b64_e32 v[30:31], 0
	v_mov_b64_e32 v[32:33], 0
	v_mov_b64_e32 v[34:35], 0
	v_mov_b64_e32 v[36:37], 0
	v_mov_b64_e32 v[38:39], 0
	v_mov_b64_e32 v[40:41], 0
	v_mov_b64_e32 v[42:43], 0
	v_mov_b64_e32 v[44:45], 0
	v_mov_b64_e32 v[46:47], 0
	v_mov_b64_e32 v[48:49], 0
	v_mov_b64_e32 v[50:51], 0
	v_mov_b64_e32 v[52:53], 0
	v_mov_b64_e32 v[54:55], 0
	v_mov_b64_e32 v[56:57], 0
	v_mov_b64_e32 v[58:59], 0
	v_mov_b64_e32 v[60:61], 0
	v_mov_b64_e32 v[62:63], 0
	v_mov_b64_e32 v[64:65], 0
	v_mov_b64_e32 v[66:67], 0
	v_mov_b64_e32 v[68:69], 0
	v_mov_b64_e32 v[70:71], 0
	v_mov_b64_e32 v[72:73], 0
	v_mov_b64_e32 v[74:75], 0
	v_mov_b64_e32 v[76:77], 0
	v_mov_b64_e32 v[78:79], 0
	v_mov_b64_e32 v[80:81], 0
	v_mov_b64_e32 v[82:83], 0
	v_mov_b64_e32 v[84:85], 0
	v_mov_b64_e32 v[86:87], 0
	v_mov_b64_e32 v[88:89], 0
	v_mov_b64_e32 v[90:91], 0
	v_mov_b64_e32 v[92:93], 0
	v_mov_b64_e32 v[94:95], 0
	v_mov_b64_e32 v[96:97], 0
	v_mov_b64_e32 v[98:99], 0
	v_mov_b64_e32 v[100:101], 0
	v_mov_b64_e32 v[102:103], 0
	v_mov_b64_e32 v[104:105], 0
	v_mov_b64_e32 v[106:107], 0
	v_mov_b64_e32 v[108:109], 0
	v_mov_b64_e32 v[110:111], 0
	v_mov_b64_e32 v[112:113], 0
	v_mov_b64_e32 v[114:115], 0
	v_mov_b64_e32 v[116:117], 0
	v_mov_b64_e32 v[118:119], 0
	v_mov_b64_e32 v[120:121], 0
	v_mov_b64_e32 v[122:123], 0
	v_mov_b64_e32 v[124:125], 0
	v_mov_b64_e32 v[126:127], 0
	s_addc_u32 s31, s31, 0
	s_mov_b32 s20, 0
.LBB0_617:
	v_add_u32_e32 v154, s87, v143
	ds_read_b128 v[138:141], v154
	ds_read_b128 v[146:149], v154 offset:1024
	ds_read_b128 v[150:153], v154 offset:2048
	ds_read_b128 v[154:157], v154 offset:3072
	s_add_i32 s25, s20, 2
	s_add_u32 s29, s30, 0x80
	s_addc_u32 s21, s31, 0
	s_cmp_eq_u32 s85, s20
	s_cselect_b32 s20, s8, s29
	s_cselect_b32 s21, s9, s21
	s_cselect_b32 s35, s11, s24
	s_cselect_b32 s34, s10, s17
	v_lshl_add_u64 v[158:159], s[30:31], 0, v[136:137]
	s_add_i32 m0, s57, 0xc000
	ds_read_b128 v[166:169], v145
	ds_read_b128 v[170:173], v145 offset:1024
	ds_read_b128 v[174:177], v145 offset:2048
	ds_read_b128 v[178:181], v145 offset:3072
	ds_read_b128 v[182:185], v145 offset:4096
	ds_read_b128 v[186:189], v145 offset:5120
	ds_read_b128 v[190:193], v145 offset:6144
	ds_read_b128 v[194:197], v145 offset:7168
	global_load_lds_dwordx4 v[158:159], off
	v_lshl_add_u64 v[158:159], s[30:31], 0, v[134:135]
	s_add_i32 m0, s57, 0xe000
	s_nop 0
	global_load_lds_dwordx4 v[158:159], off
	s_waitcnt lgkmcnt(8)
	s_barrier
	s_waitcnt lgkmcnt(0)
	s_waitcnt lgkmcnt(0)
	v_mfma_f32_16x16x32_bf16 v[124:127], v[138:141], v[166:169], v[124:127]
	v_mfma_f32_16x16x32_bf16 v[120:123], v[150:153], v[166:169], v[120:123]
	v_mfma_f32_16x16x32_bf16 v[108:111], v[138:141], v[174:177], v[108:111]
	v_mfma_f32_16x16x32_bf16 v[104:107], v[150:153], v[174:177], v[104:107]
	v_mfma_f32_16x16x32_bf16 v[92:95], v[138:141], v[182:185], v[92:95]
	v_mfma_f32_16x16x32_bf16 v[88:91], v[150:153], v[182:185], v[88:91]
	v_mfma_f32_16x16x32_bf16 v[76:79], v[138:141], v[190:193], v[76:79]
	v_mfma_f32_16x16x32_bf16 v[72:75], v[150:153], v[190:193], v[72:75]
	v_mfma_f32_16x16x32_bf16 v[124:127], v[146:149], v[170:173], v[124:127]
	v_mfma_f32_16x16x32_bf16 v[120:123], v[154:157], v[170:173], v[120:123]
	v_mfma_f32_16x16x32_bf16 v[108:111], v[146:149], v[178:181], v[108:111]
	v_mfma_f32_16x16x32_bf16 v[104:107], v[154:157], v[178:181], v[104:107]
	v_mfma_f32_16x16x32_bf16 v[92:95], v[146:149], v[186:189], v[92:95]
	v_mfma_f32_16x16x32_bf16 v[88:91], v[154:157], v[186:189], v[88:91]
	v_mfma_f32_16x16x32_bf16 v[76:79], v[146:149], v[194:197], v[76:79]
	v_mfma_f32_16x16x32_bf16 v[72:75], v[154:157], v[194:197], v[72:75]
	s_barrier
	s_add_i32 s29, 0, 0x14000
	v_add_u32_e32 v158, s29, v143
	s_add_i32 s36, s87, s45
	ds_read_b128 v[198:201], v158
	ds_read_b128 v[232:235], v158 offset:1024
	ds_read_b128 v[236:239], v158 offset:2048
	ds_read_b128 v[240:243], v158 offset:3072
	v_lshl_add_u64 v[158:159], s[34:35], 0, v[160:161]
	s_mov_b32 m0, s36
	v_lshl_add_u64 v[202:203], s[34:35], 0, v[132:133]
	global_load_lds_dwordx4 v[158:159], off
	s_add_i32 m0, s36, 0x2000
	s_nop 0
	global_load_lds_dwordx4 v[202:203], off
	s_barrier
	s_waitcnt lgkmcnt(0)
	s_waitcnt lgkmcnt(0)
	v_mfma_f32_16x16x32_bf16 v[116:119], v[198:201], v[166:169], v[116:119]
	v_mfma_f32_16x16x32_bf16 v[112:115], v[236:239], v[166:169], v[112:115]
	v_mfma_f32_16x16x32_bf16 v[100:103], v[198:201], v[174:177], v[100:103]
	v_mfma_f32_16x16x32_bf16 v[96:99], v[236:239], v[174:177], v[96:99]
	v_mfma_f32_16x16x32_bf16 v[84:87], v[198:201], v[182:185], v[84:87]
	v_mfma_f32_16x16x32_bf16 v[80:83], v[236:239], v[182:185], v[80:83]
	v_mfma_f32_16x16x32_bf16 v[68:71], v[198:201], v[190:193], v[68:71]
	v_mfma_f32_16x16x32_bf16 v[64:67], v[236:239], v[190:193], v[64:67]
	v_mfma_f32_16x16x32_bf16 v[116:119], v[232:235], v[170:173], v[116:119]
	v_mfma_f32_16x16x32_bf16 v[112:115], v[240:243], v[170:173], v[112:115]
	v_mfma_f32_16x16x32_bf16 v[100:103], v[232:235], v[178:181], v[100:103]
	v_mfma_f32_16x16x32_bf16 v[96:99], v[240:243], v[178:181], v[96:99]
	v_mfma_f32_16x16x32_bf16 v[84:87], v[232:235], v[186:189], v[84:87]
	v_mfma_f32_16x16x32_bf16 v[80:83], v[240:243], v[186:189], v[80:83]
	v_mfma_f32_16x16x32_bf16 v[68:71], v[232:235], v[194:197], v[68:71]
	v_mfma_f32_16x16x32_bf16 v[64:67], v[240:243], v[194:197], v[64:67]
	s_mov_b32 m0, s57
	v_lshl_add_u64 v[206:207], s[20:21], 0, v[128:129]
	s_barrier
	ds_read_b128 v[166:169], v145 offset:16384
	ds_read_b128 v[170:173], v145 offset:17408
	ds_read_b128 v[174:177], v145 offset:18432
	ds_read_b128 v[178:181], v145 offset:19456
	ds_read_b128 v[182:185], v145 offset:20480
	ds_read_b128 v[186:189], v145 offset:21504
	ds_read_b128 v[190:193], v145 offset:22528
	ds_read_b128 v[194:197], v145 offset:23552
	global_load_lds_dwordx4 v[206:207], off
	v_lshl_add_u64 v[210:211], s[20:21], 0, v[130:131]
	s_mov_b32 m0, s26
	s_nop 0
	global_load_lds_dwordx4 v[210:211], off
	s_barrier
	s_waitcnt lgkmcnt(0)
	s_waitcnt lgkmcnt(0)
	v_mfma_f32_16x16x32_bf16 v[60:63], v[138:141], v[166:169], v[60:63]
	v_mfma_f32_16x16x32_bf16 v[56:59], v[150:153], v[166:169], v[56:59]
	v_mfma_f32_16x16x32_bf16 v[44:47], v[138:141], v[174:177], v[44:47]
	v_mfma_f32_16x16x32_bf16 v[40:43], v[150:153], v[174:177], v[40:43]
	v_mfma_f32_16x16x32_bf16 v[28:31], v[138:141], v[182:185], v[28:31]
	v_mfma_f32_16x16x32_bf16 v[24:27], v[150:153], v[182:185], v[24:27]
	v_mfma_f32_16x16x32_bf16 v[12:15], v[138:141], v[190:193], v[12:15]
	v_mfma_f32_16x16x32_bf16 v[8:11], v[150:153], v[190:193], v[8:11]
	v_mfma_f32_16x16x32_bf16 v[60:63], v[146:149], v[170:173], v[60:63]
	v_mfma_f32_16x16x32_bf16 v[56:59], v[154:157], v[170:173], v[56:59]
	v_mfma_f32_16x16x32_bf16 v[44:47], v[146:149], v[178:181], v[44:47]
	v_mfma_f32_16x16x32_bf16 v[40:43], v[154:157], v[178:181], v[40:43]
	v_mfma_f32_16x16x32_bf16 v[28:31], v[146:149], v[186:189], v[28:31]
	v_mfma_f32_16x16x32_bf16 v[24:27], v[154:157], v[186:189], v[24:27]
	v_mfma_f32_16x16x32_bf16 v[12:15], v[146:149], v[194:197], v[12:15]
	v_mfma_f32_16x16x32_bf16 v[8:11], v[154:157], v[194:197], v[8:11]
	s_barrier
	s_add_u32 s34, s34, s64
	s_addc_u32 s35, s35, s65
	s_add_i32 s29, s29, s45
	v_lshl_add_u64 v[244:245], s[34:35], 0, v[160:161]
	s_mov_b32 m0, s29
	v_lshl_add_u64 v[246:247], s[34:35], 0, v[132:133]
	global_load_lds_dwordx4 v[244:245], off
	s_add_i32 m0, s29, 0x2000
	s_nop 0
	global_load_lds_dwordx4 v[246:247], off
	s_waitcnt vmcnt(6)
	s_barrier
	v_mfma_f32_16x16x32_bf16 v[52:55], v[198:201], v[166:169], v[52:55]
	v_mfma_f32_16x16x32_bf16 v[48:51], v[236:239], v[166:169], v[48:51]
	v_mfma_f32_16x16x32_bf16 v[36:39], v[198:201], v[174:177], v[36:39]
	v_mfma_f32_16x16x32_bf16 v[32:35], v[236:239], v[174:177], v[32:35]
	v_mfma_f32_16x16x32_bf16 v[20:23], v[198:201], v[182:185], v[20:23]
	v_mfma_f32_16x16x32_bf16 v[16:19], v[236:239], v[182:185], v[16:19]
	v_mfma_f32_16x16x32_bf16 v[4:7], v[198:201], v[190:193], v[4:7]
	v_mfma_f32_16x16x32_bf16 v[0:3], v[236:239], v[190:193], v[0:3]
	v_mfma_f32_16x16x32_bf16 v[52:55], v[232:235], v[170:173], v[52:55]
	v_mfma_f32_16x16x32_bf16 v[48:51], v[240:243], v[170:173], v[48:51]
	v_mfma_f32_16x16x32_bf16 v[36:39], v[232:235], v[178:181], v[36:39]
	v_mfma_f32_16x16x32_bf16 v[32:35], v[240:243], v[178:181], v[32:35]
	v_mfma_f32_16x16x32_bf16 v[20:23], v[232:235], v[186:189], v[20:23]
	v_mfma_f32_16x16x32_bf16 v[16:19], v[240:243], v[186:189], v[16:19]
	v_mfma_f32_16x16x32_bf16 v[4:7], v[232:235], v[194:197], v[4:7]
	v_mfma_f32_16x16x32_bf16 v[0:3], v[240:243], v[194:197], v[0:3]
	s_add_i32 s29, 0, 0x18000
	v_add_u32_e32 v154, s29, v143
	s_barrier
	ds_read_b128 v[138:141], v154
	ds_read_b128 v[146:149], v154 offset:1024
	ds_read_b128 v[150:153], v154 offset:2048
	ds_read_b128 v[154:157], v154 offset:3072
	s_add_u32 s20, s20, s64
	s_addc_u32 s21, s21, s65
	s_mov_b32 m0, s27
	v_lshl_add_u64 v[198:199], s[20:21], 0, v[128:129]
	ds_read_b128 v[166:169], v145 offset:32768
	ds_read_b128 v[170:173], v145 offset:33792
	ds_read_b128 v[174:177], v145 offset:34816
	ds_read_b128 v[178:181], v145 offset:35840
	ds_read_b128 v[182:185], v145 offset:36864
	ds_read_b128 v[186:189], v145 offset:37888
	ds_read_b128 v[190:193], v145 offset:38912
	ds_read_b128 v[194:197], v145 offset:39936
	global_load_lds_dwordx4 v[198:199], off
	v_lshl_add_u64 v[198:199], s[20:21], 0, v[130:131]
	s_mov_b32 m0, s54
	s_nop 0
	global_load_lds_dwordx4 v[198:199], off
	s_waitcnt lgkmcnt(8)
	s_barrier
	s_waitcnt lgkmcnt(0)
	s_waitcnt lgkmcnt(0)
	v_mfma_f32_16x16x32_bf16 v[124:127], v[138:141], v[166:169], v[124:127]
	v_mfma_f32_16x16x32_bf16 v[120:123], v[150:153], v[166:169], v[120:123]
	v_mfma_f32_16x16x32_bf16 v[108:111], v[138:141], v[174:177], v[108:111]
	v_mfma_f32_16x16x32_bf16 v[104:107], v[150:153], v[174:177], v[104:107]
	v_mfma_f32_16x16x32_bf16 v[92:95], v[138:141], v[182:185], v[92:95]
	v_mfma_f32_16x16x32_bf16 v[88:91], v[150:153], v[182:185], v[88:91]
	v_mfma_f32_16x16x32_bf16 v[76:79], v[138:141], v[190:193], v[76:79]
	v_mfma_f32_16x16x32_bf16 v[72:75], v[150:153], v[190:193], v[72:75]
	v_mfma_f32_16x16x32_bf16 v[124:127], v[146:149], v[170:173], v[124:127]
	v_mfma_f32_16x16x32_bf16 v[120:123], v[154:157], v[170:173], v[120:123]
	v_mfma_f32_16x16x32_bf16 v[108:111], v[146:149], v[178:181], v[108:111]
	v_mfma_f32_16x16x32_bf16 v[104:107], v[154:157], v[178:181], v[104:107]
	v_mfma_f32_16x16x32_bf16 v[92:95], v[146:149], v[186:189], v[92:95]
	v_mfma_f32_16x16x32_bf16 v[88:91], v[154:157], v[186:189], v[88:91]
	v_mfma_f32_16x16x32_bf16 v[76:79], v[146:149], v[194:197], v[76:79]
	v_mfma_f32_16x16x32_bf16 v[72:75], v[154:157], v[194:197], v[72:75]
	s_barrier
	s_add_i32 s20, 0, 0x1c000
	s_add_i32 s21, s29, s45
	v_add_u32_e32 v240, s20, v143
	v_lshl_add_u64 v[158:159], v[158:159], 0, s[96:97]
	s_mov_b32 m0, s21
	ds_read_b128 v[198:201], v240
	ds_read_b128 v[232:235], v240 offset:1024
	ds_read_b128 v[236:239], v240 offset:2048
	ds_read_b128 v[240:243], v240 offset:3072
	global_load_lds_dwordx4 v[158:159], off
	v_lshl_add_u64 v[158:159], v[202:203], 0, s[96:97]
	s_add_i32 m0, s21, 0x2000
	s_nop 0
	global_load_lds_dwordx4 v[158:159], off
	s_barrier
	s_waitcnt lgkmcnt(0)
	s_waitcnt lgkmcnt(0)
	v_mfma_f32_16x16x32_bf16 v[116:119], v[198:201], v[166:169], v[116:119]
	v_mfma_f32_16x16x32_bf16 v[112:115], v[236:239], v[166:169], v[112:115]
	v_mfma_f32_16x16x32_bf16 v[100:103], v[198:201], v[174:177], v[100:103]
	v_mfma_f32_16x16x32_bf16 v[96:99], v[236:239], v[174:177], v[96:99]
	v_mfma_f32_16x16x32_bf16 v[84:87], v[198:201], v[182:185], v[84:87]
	v_mfma_f32_16x16x32_bf16 v[80:83], v[236:239], v[182:185], v[80:83]
	v_mfma_f32_16x16x32_bf16 v[68:71], v[198:201], v[190:193], v[68:71]
	v_mfma_f32_16x16x32_bf16 v[64:67], v[236:239], v[190:193], v[64:67]
	v_mfma_f32_16x16x32_bf16 v[116:119], v[232:235], v[170:173], v[116:119]
	v_mfma_f32_16x16x32_bf16 v[112:115], v[240:243], v[170:173], v[112:115]
	v_mfma_f32_16x16x32_bf16 v[100:103], v[232:235], v[178:181], v[100:103]
	v_mfma_f32_16x16x32_bf16 v[96:99], v[240:243], v[178:181], v[96:99]
	v_mfma_f32_16x16x32_bf16 v[84:87], v[232:235], v[186:189], v[84:87]
	v_mfma_f32_16x16x32_bf16 v[80:83], v[240:243], v[186:189], v[80:83]
	v_mfma_f32_16x16x32_bf16 v[68:71], v[232:235], v[194:197], v[68:71]
	v_mfma_f32_16x16x32_bf16 v[64:67], v[240:243], v[194:197], v[64:67]
	s_mov_b32 m0, s55
	v_lshl_add_u64 v[158:159], v[206:207], 0, s[96:97]
	s_barrier
	ds_read_b128 v[166:169], v145 offset:49152
	ds_read_b128 v[170:173], v145 offset:50176
	ds_read_b128 v[174:177], v145 offset:51200
	ds_read_b128 v[178:181], v145 offset:52224
	ds_read_b128 v[182:185], v145 offset:53248
	ds_read_b128 v[186:189], v145 offset:54272
	ds_read_b128 v[190:193], v145 offset:55296
	ds_read_b128 v[194:197], v145 offset:56320
	global_load_lds_dwordx4 v[158:159], off
	v_lshl_add_u64 v[158:159], v[210:211], 0, s[96:97]
	s_mov_b32 m0, s84
	s_nop 0
	global_load_lds_dwordx4 v[158:159], off
	s_barrier
	s_waitcnt lgkmcnt(0)
	s_waitcnt lgkmcnt(0)
	v_mfma_f32_16x16x32_bf16 v[60:63], v[138:141], v[166:169], v[60:63]
	v_mfma_f32_16x16x32_bf16 v[56:59], v[150:153], v[166:169], v[56:59]
	v_mfma_f32_16x16x32_bf16 v[44:47], v[138:141], v[174:177], v[44:47]
	v_mfma_f32_16x16x32_bf16 v[40:43], v[150:153], v[174:177], v[40:43]
	v_mfma_f32_16x16x32_bf16 v[28:31], v[138:141], v[182:185], v[28:31]
	v_mfma_f32_16x16x32_bf16 v[24:27], v[150:153], v[182:185], v[24:27]
	v_mfma_f32_16x16x32_bf16 v[12:15], v[138:141], v[190:193], v[12:15]
	v_mfma_f32_16x16x32_bf16 v[8:11], v[150:153], v[190:193], v[8:11]
	v_mfma_f32_16x16x32_bf16 v[60:63], v[146:149], v[170:173], v[60:63]
	v_mfma_f32_16x16x32_bf16 v[56:59], v[154:157], v[170:173], v[56:59]
	v_mfma_f32_16x16x32_bf16 v[44:47], v[146:149], v[178:181], v[44:47]
	v_mfma_f32_16x16x32_bf16 v[40:43], v[154:157], v[178:181], v[40:43]
	v_mfma_f32_16x16x32_bf16 v[28:31], v[146:149], v[186:189], v[28:31]
	v_mfma_f32_16x16x32_bf16 v[24:27], v[154:157], v[186:189], v[24:27]
	v_mfma_f32_16x16x32_bf16 v[12:15], v[146:149], v[194:197], v[12:15]
	v_mfma_f32_16x16x32_bf16 v[8:11], v[154:157], v[194:197], v[8:11]
	s_barrier
	s_add_i32 s20, s20, s45
	v_lshl_add_u64 v[138:139], v[244:245], 0, s[96:97]
	s_mov_b32 m0, s20
	s_nop 0
	global_load_lds_dwordx4 v[138:139], off
	v_lshl_add_u64 v[138:139], v[246:247], 0, s[96:97]
	s_add_i32 m0, s20, 0x2000
	s_nop 0
	global_load_lds_dwordx4 v[138:139], off
	s_waitcnt vmcnt(6)
	s_barrier
	v_mfma_f32_16x16x32_bf16 v[52:55], v[198:201], v[166:169], v[52:55]
	v_mfma_f32_16x16x32_bf16 v[48:51], v[236:239], v[166:169], v[48:51]
	v_mfma_f32_16x16x32_bf16 v[36:39], v[198:201], v[174:177], v[36:39]
	v_mfma_f32_16x16x32_bf16 v[32:35], v[236:239], v[174:177], v[32:35]
	v_mfma_f32_16x16x32_bf16 v[20:23], v[198:201], v[182:185], v[20:23]
	v_mfma_f32_16x16x32_bf16 v[16:19], v[236:239], v[182:185], v[16:19]
	v_mfma_f32_16x16x32_bf16 v[4:7], v[198:201], v[190:193], v[4:7]
	v_mfma_f32_16x16x32_bf16 v[0:3], v[236:239], v[190:193], v[0:3]
	v_mfma_f32_16x16x32_bf16 v[52:55], v[232:235], v[170:173], v[52:55]
	v_mfma_f32_16x16x32_bf16 v[48:51], v[240:243], v[170:173], v[48:51]
	v_mfma_f32_16x16x32_bf16 v[36:39], v[232:235], v[178:181], v[36:39]
	v_mfma_f32_16x16x32_bf16 v[32:35], v[240:243], v[178:181], v[32:35]
	v_mfma_f32_16x16x32_bf16 v[20:23], v[232:235], v[186:189], v[20:23]
	v_mfma_f32_16x16x32_bf16 v[16:19], v[240:243], v[186:189], v[16:19]
	v_mfma_f32_16x16x32_bf16 v[4:7], v[232:235], v[194:197], v[4:7]
	v_mfma_f32_16x16x32_bf16 v[0:3], v[240:243], v[194:197], v[0:3]
	s_add_u32 s17, s17, 0x100
	s_addc_u32 s24, s24, 0
	s_add_u32 s30, s30, 0x100
	s_addc_u32 s31, s31, 0
	s_cmp_ge_i32 s25, s41
	s_mov_b32 s20, s25
	s_barrier
	s_cbranch_scc0 .LBB0_617
	v_readlane_b32 s20, v254, 5
	v_mov_b32 v138, s20
	v_readlane_b32 s21, v254, 6
	v_readfirstlane_b32 s17, v138
	v_mov_b32 v138, s21
	s_add_u32 s20, s17, 0xc400000
	v_readfirstlane_b32 s24, v138
	s_addc_u32 s21, s24, 0
	s_mov_b64 s[36:37], -1
	s_mov_b64 s[34:35], 0
	s_cmp_lt_i32 s2, 5
	s_mov_b64 s[30:31], 0
	s_mov_b64 s[38:39], 0
	s_cbranch_scc1 .LBB0_622
	s_mov_b64 s[38:39], -1
	s_mov_b64 s[36:37], 0
	s_cmp_gt_i32 s2, 5
	s_cbranch_scc0 .LBB0_622
	s_cmp_gt_i32 s2, 6
	s_cbranch_scc0 .LBB0_640
	s_cmp_eq_u32 s2, 7
	s_cselect_b64 s[38:39], -1, 0

.LBB0_667:
	s_add_i32 s94, s24, 1
	s_mul_i32 s6, s94, s91
	s_mul_hi_u32 s7, s94, s33
	s_add_i32 s7, s7, s6
	s_mul_i32 s6, s94, s33
	s_add_u32 s10, s6, s47
	s_addc_u32 s11, s7, s49
	v_mov_b64_e32 v[0:1], s[58:59]
	v_cmp_ge_i64_e64 s[6:7], s[10:11], v[0:1]
	v_cmp_lt_i64_e64 s[8:9], s[10:11], v[0:1]
	s_and_b64 vcc, exec, s[6:7]
	s_cbranch_vccnz .LBB0_673
	s_and_b32 s16, s10, 7
	s_lshl_b32 s16, s16, 3
	s_bfe_u32 s25, s10, 0x30003
	s_or_b32 s16, s16, s25
	s_lshr_b32 s95, s10, 6

.LBB0_677:
	s_add_u32 s25, s20, 0x100
	s_addc_u32 s38, s21, 0
	s_add_u32 s30, s30, 0x80
	v_mov_b64_e32 v[0:1], 0
	v_mov_b64_e32 v[2:3], 0
	v_mov_b64_e32 v[4:5], 0
	v_mov_b64_e32 v[6:7], 0
	v_mov_b64_e32 v[8:9], 0
	v_mov_b64_e32 v[10:11], 0
	v_mov_b64_e32 v[12:13], 0
	v_mov_b64_e32 v[14:15], 0
	v_mov_b64_e32 v[16:17], 0
	v_mov_b64_e32 v[18:19], 0
	v_mov_b64_e32 v[20:21], 0
	v_mov_b64_e32 v[22:23], 0
	v_mov_b64_e32 v[24:25], 0
	v_mov_b64_e32 v[26:27], 0
	v_mov_b64_e32 v[28:29], 0
	v_mov_b64_e32 v[30:31], 0
	v_mov_b64_e32 v[32:33], 0
	v_mov_b64_e32 v[34:35], 0
	v_mov_b64_e32 v[36:37], 0
	v_mov_b64_e32 v[38:39], 0
	v_mov_b64_e32 v[40:41], 0
	v_mov_b64_e32 v[42:43], 0
	v_mov_b64_e32 v[44:45], 0
	v_mov_b64_e32 v[46:47], 0
	v_mov_b64_e32 v[48:49], 0
	v_mov_b64_e32 v[50:51], 0
	v_mov_b64_e32 v[52:53], 0
	v_mov_b64_e32 v[54:55], 0
	v_mov_b64_e32 v[56:57], 0
	v_mov_b64_e32 v[58:59], 0
	v_mov_b64_e32 v[60:61], 0
	v_mov_b64_e32 v[62:63], 0
	v_mov_b64_e32 v[64:65], 0
	v_mov_b64_e32 v[66:67], 0
	v_mov_b64_e32 v[68:69], 0
	v_mov_b64_e32 v[70:71], 0
	v_mov_b64_e32 v[72:73], 0
	v_mov_b64_e32 v[74:75], 0
	v_mov_b64_e32 v[76:77], 0
	v_mov_b64_e32 v[78:79], 0
	v_mov_b64_e32 v[84:85], 0
	v_mov_b64_e32 v[86:87], 0
	v_mov_b64_e32 v[88:89], 0
	v_mov_b64_e32 v[90:91], 0
	v_mov_b64_e32 v[92:93], 0
	v_mov_b64_e32 v[94:95], 0
	v_mov_b64_e32 v[96:97], 0
	v_mov_b64_e32 v[98:99], 0
	v_mov_b64_e32 v[100:101], 0
	v_mov_b64_e32 v[102:103], 0
	v_mov_b64_e32 v[104:105], 0
	v_mov_b64_e32 v[106:107], 0
	v_mov_b64_e32 v[108:109], 0
	v_mov_b64_e32 v[110:111], 0
	v_mov_b64_e32 v[116:117], 0
	v_mov_b64_e32 v[118:119], 0
	v_mov_b64_e32 v[120:121], 0
	v_mov_b64_e32 v[122:123], 0
	v_mov_b64_e32 v[124:125], 0
	v_mov_b64_e32 v[126:127], 0
	v_mov_b64_e32 v[128:129], 0
	v_mov_b64_e32 v[130:131], 0
	v_mov_b64_e32 v[132:133], 0
	v_mov_b64_e32 v[134:135], 0
	s_addc_u32 s31, s31, 0
	s_mov_b32 s20, 0
.LBB0_678:
	v_add_u32_e32 v140, s87, v159
	ds_read_b128 v[80:83], v140
	ds_read_b128 v[112:115], v140 offset:1024
	ds_read_b128 v[136:139], v140 offset:2048
	ds_read_b128 v[140:143], v140 offset:3072
	s_add_i32 s39, s20, 2
	s_add_u32 s34, s30, 0x80
	s_addc_u32 s21, s31, 0
	s_cmp_eq_u32 s48, s20
	s_cselect_b32 s20, s36, s34
	s_cselect_b32 s21, s37, s21
	s_cselect_b32 s35, s11, s38
	s_cselect_b32 s34, s10, s25
	v_lshl_add_u64 v[156:157], s[30:31], 0, v[154:155]
	s_add_i32 m0, s23, 0xc000
	ds_read_b128 v[170:173], v168
	ds_read_b128 v[174:177], v168 offset:1024
	ds_read_b128 v[178:181], v168 offset:2048
	ds_read_b128 v[182:185], v168 offset:3072
	ds_read_b128 v[186:189], v168 offset:4096
	ds_read_b128 v[190:193], v168 offset:5120
	ds_read_b128 v[194:197], v168 offset:6144
	ds_read_b128 v[198:201], v168 offset:7168
	global_load_lds_dwordx4 v[156:157], off
	v_lshl_add_u64 v[156:157], s[30:31], 0, v[152:153]
	s_add_i32 m0, s23, 0xe000
	s_nop 0
	global_load_lds_dwordx4 v[156:157], off
	s_waitcnt lgkmcnt(8)
	s_barrier
	s_waitcnt lgkmcnt(0)
	s_waitcnt lgkmcnt(0)
	v_mfma_f32_16x16x32_bf16 v[132:135], v[80:83], v[170:173], v[132:135]
	v_mfma_f32_16x16x32_bf16 v[124:127], v[136:139], v[170:173], v[124:127]
	v_mfma_f32_16x16x32_bf16 v[116:119], v[80:83], v[178:181], v[116:119]
	v_mfma_f32_16x16x32_bf16 v[104:107], v[136:139], v[178:181], v[104:107]
	v_mfma_f32_16x16x32_bf16 v[96:99], v[80:83], v[186:189], v[96:99]
	v_mfma_f32_16x16x32_bf16 v[88:91], v[136:139], v[186:189], v[88:91]
	v_mfma_f32_16x16x32_bf16 v[76:79], v[80:83], v[194:197], v[76:79]
	v_mfma_f32_16x16x32_bf16 v[68:71], v[136:139], v[194:197], v[68:71]
	v_mfma_f32_16x16x32_bf16 v[132:135], v[112:115], v[174:177], v[132:135]
	v_mfma_f32_16x16x32_bf16 v[124:127], v[140:143], v[174:177], v[124:127]
	v_mfma_f32_16x16x32_bf16 v[116:119], v[112:115], v[182:185], v[116:119]
	v_mfma_f32_16x16x32_bf16 v[104:107], v[140:143], v[182:185], v[104:107]
	v_mfma_f32_16x16x32_bf16 v[96:99], v[112:115], v[190:193], v[96:99]
	v_mfma_f32_16x16x32_bf16 v[88:91], v[140:143], v[190:193], v[88:91]
	v_mfma_f32_16x16x32_bf16 v[76:79], v[112:115], v[198:201], v[76:79]
	v_mfma_f32_16x16x32_bf16 v[68:71], v[140:143], v[198:201], v[68:71]
	s_barrier
	s_add_i32 s42, 0, 0x14000
	v_add_u32_e32 v156, s42, v159
	s_add_i32 s43, s87, s22
	ds_read_b128 v[232:235], v156
	ds_read_b128 v[236:239], v156 offset:1024
	ds_read_b128 v[240:243], v156 offset:2048
	ds_read_b128 v[244:247], v156 offset:3072
	v_lshl_add_u64 v[156:157], s[34:35], 0, v[160:161]
	s_mov_b32 m0, s43
	v_lshl_add_u64 v[202:203], s[34:35], 0, v[148:149]
	global_load_lds_dwordx4 v[156:157], off
	s_add_i32 m0, s43, 0x2000
	s_nop 0
	global_load_lds_dwordx4 v[202:203], off
	s_barrier
	s_waitcnt lgkmcnt(0)
	s_waitcnt lgkmcnt(0)
	v_mfma_f32_16x16x32_bf16 v[128:131], v[232:235], v[170:173], v[128:131]
	v_mfma_f32_16x16x32_bf16 v[120:123], v[240:243], v[170:173], v[120:123]
	v_mfma_f32_16x16x32_bf16 v[108:111], v[232:235], v[178:181], v[108:111]
	v_mfma_f32_16x16x32_bf16 v[100:103], v[240:243], v[178:181], v[100:103]
	v_mfma_f32_16x16x32_bf16 v[92:95], v[232:235], v[186:189], v[92:95]
	v_mfma_f32_16x16x32_bf16 v[84:87], v[240:243], v[186:189], v[84:87]
	v_mfma_f32_16x16x32_bf16 v[72:75], v[232:235], v[194:197], v[72:75]
	v_mfma_f32_16x16x32_bf16 v[64:67], v[240:243], v[194:197], v[64:67]
	v_mfma_f32_16x16x32_bf16 v[128:131], v[236:239], v[174:177], v[128:131]
	v_mfma_f32_16x16x32_bf16 v[120:123], v[244:247], v[174:177], v[120:123]
	v_mfma_f32_16x16x32_bf16 v[108:111], v[236:239], v[182:185], v[108:111]
	v_mfma_f32_16x16x32_bf16 v[100:103], v[244:247], v[182:185], v[100:103]
	v_mfma_f32_16x16x32_bf16 v[92:95], v[236:239], v[190:193], v[92:95]
	v_mfma_f32_16x16x32_bf16 v[84:87], v[244:247], v[190:193], v[84:87]
	v_mfma_f32_16x16x32_bf16 v[72:75], v[236:239], v[198:201], v[72:75]
	v_mfma_f32_16x16x32_bf16 v[64:67], v[244:247], v[198:201], v[64:67]
	s_mov_b32 m0, s23
	v_lshl_add_u64 v[206:207], s[20:21], 0, v[144:145]
	s_barrier
	ds_read_b128 v[170:173], v168 offset:16384
	ds_read_b128 v[174:177], v168 offset:17408
	ds_read_b128 v[178:181], v168 offset:18432
	ds_read_b128 v[182:185], v168 offset:19456
	ds_read_b128 v[186:189], v168 offset:20480
	ds_read_b128 v[190:193], v168 offset:21504
	ds_read_b128 v[194:197], v168 offset:22528
	ds_read_b128 v[198:201], v168 offset:23552
	global_load_lds_dwordx4 v[206:207], off
	v_lshl_add_u64 v[248:249], s[20:21], 0, v[146:147]
	s_mov_b32 m0, s27
	s_nop 0
	global_load_lds_dwordx4 v[248:249], off
	s_barrier
	s_waitcnt lgkmcnt(0)
	s_waitcnt lgkmcnt(0)
	v_mfma_f32_16x16x32_bf16 v[60:63], v[80:83], v[170:173], v[60:63]
	v_mfma_f32_16x16x32_bf16 v[52:55], v[136:139], v[170:173], v[52:55]
	v_mfma_f32_16x16x32_bf16 v[44:47], v[80:83], v[178:181], v[44:47]
	v_mfma_f32_16x16x32_bf16 v[36:39], v[136:139], v[178:181], v[36:39]
	v_mfma_f32_16x16x32_bf16 v[28:31], v[80:83], v[186:189], v[28:31]
	v_mfma_f32_16x16x32_bf16 v[20:23], v[136:139], v[186:189], v[20:23]
	v_mfma_f32_16x16x32_bf16 v[12:15], v[80:83], v[194:197], v[12:15]
	v_mfma_f32_16x16x32_bf16 v[4:7], v[136:139], v[194:197], v[4:7]
	v_mfma_f32_16x16x32_bf16 v[60:63], v[112:115], v[174:177], v[60:63]
	v_mfma_f32_16x16x32_bf16 v[52:55], v[140:143], v[174:177], v[52:55]
	v_mfma_f32_16x16x32_bf16 v[44:47], v[112:115], v[182:185], v[44:47]
	v_mfma_f32_16x16x32_bf16 v[36:39], v[140:143], v[182:185], v[36:39]
	v_mfma_f32_16x16x32_bf16 v[28:31], v[112:115], v[190:193], v[28:31]
	v_mfma_f32_16x16x32_bf16 v[20:23], v[140:143], v[190:193], v[20:23]
	v_mfma_f32_16x16x32_bf16 v[12:15], v[112:115], v[198:201], v[12:15]
	v_mfma_f32_16x16x32_bf16 v[4:7], v[140:143], v[198:201], v[4:7]
	s_barrier
	s_add_u32 s34, s34, s64
	s_addc_u32 s35, s35, s65
	s_add_i32 s42, s42, s22
	v_lshl_add_u64 v[250:251], s[34:35], 0, v[160:161]
	s_mov_b32 m0, s42
	v_lshl_add_u64 v[210:211], s[34:35], 0, v[148:149]
	global_load_lds_dwordx4 v[250:251], off
	s_add_i32 m0, s42, 0x2000
	s_nop 0
	global_load_lds_dwordx4 v[210:211], off
	s_waitcnt vmcnt(6)
	s_barrier
	v_mfma_f32_16x16x32_bf16 v[56:59], v[232:235], v[170:173], v[56:59]
	v_mfma_f32_16x16x32_bf16 v[48:51], v[240:243], v[170:173], v[48:51]
	v_mfma_f32_16x16x32_bf16 v[40:43], v[232:235], v[178:181], v[40:43]
	v_mfma_f32_16x16x32_bf16 v[32:35], v[240:243], v[178:181], v[32:35]
	v_mfma_f32_16x16x32_bf16 v[24:27], v[232:235], v[186:189], v[24:27]
	v_mfma_f32_16x16x32_bf16 v[16:19], v[240:243], v[186:189], v[16:19]
	v_mfma_f32_16x16x32_bf16 v[8:11], v[232:235], v[194:197], v[8:11]
	v_mfma_f32_16x16x32_bf16 v[0:3], v[240:243], v[194:197], v[0:3]
	v_mfma_f32_16x16x32_bf16 v[56:59], v[236:239], v[174:177], v[56:59]
	v_mfma_f32_16x16x32_bf16 v[48:51], v[244:247], v[174:177], v[48:51]
	v_mfma_f32_16x16x32_bf16 v[40:43], v[236:239], v[182:185], v[40:43]
	v_mfma_f32_16x16x32_bf16 v[32:35], v[244:247], v[182:185], v[32:35]
	v_mfma_f32_16x16x32_bf16 v[24:27], v[236:239], v[190:193], v[24:27]
	v_mfma_f32_16x16x32_bf16 v[16:19], v[244:247], v[190:193], v[16:19]
	v_mfma_f32_16x16x32_bf16 v[8:11], v[236:239], v[198:201], v[8:11]
	v_mfma_f32_16x16x32_bf16 v[0:3], v[244:247], v[198:201], v[0:3]
	s_add_i32 s34, 0, 0x18000
	v_add_u32_e32 v140, s34, v159
	s_barrier
	ds_read_b128 v[80:83], v140
	ds_read_b128 v[112:115], v140 offset:1024
	ds_read_b128 v[136:139], v140 offset:2048
	ds_read_b128 v[140:143], v140 offset:3072
	s_add_u32 s20, s20, s64
	s_addc_u32 s21, s21, s65
	s_mov_b32 m0, s28
	v_lshl_add_u64 v[232:233], s[20:21], 0, v[144:145]
	ds_read_b128 v[170:173], v168 offset:32768
	ds_read_b128 v[174:177], v168 offset:33792
	ds_read_b128 v[178:181], v168 offset:34816
	ds_read_b128 v[182:185], v168 offset:35840
	ds_read_b128 v[186:189], v168 offset:36864
	ds_read_b128 v[190:193], v168 offset:37888
	ds_read_b128 v[194:197], v168 offset:38912
	ds_read_b128 v[198:201], v168 offset:39936
	global_load_lds_dwordx4 v[232:233], off
	v_lshl_add_u64 v[232:233], s[20:21], 0, v[146:147]
	s_mov_b32 m0, s29
	s_nop 0
	global_load_lds_dwordx4 v[232:233], off
	s_waitcnt lgkmcnt(8)
	s_barrier
	s_waitcnt lgkmcnt(0)
	s_waitcnt lgkmcnt(0)
	v_mfma_f32_16x16x32_bf16 v[132:135], v[80:83], v[170:173], v[132:135]
	v_mfma_f32_16x16x32_bf16 v[124:127], v[136:139], v[170:173], v[124:127]
	v_mfma_f32_16x16x32_bf16 v[116:119], v[80:83], v[178:181], v[116:119]
	v_mfma_f32_16x16x32_bf16 v[104:107], v[136:139], v[178:181], v[104:107]
	v_mfma_f32_16x16x32_bf16 v[96:99], v[80:83], v[186:189], v[96:99]
	v_mfma_f32_16x16x32_bf16 v[88:91], v[136:139], v[186:189], v[88:91]
	v_mfma_f32_16x16x32_bf16 v[76:79], v[80:83], v[194:197], v[76:79]
	v_mfma_f32_16x16x32_bf16 v[68:71], v[136:139], v[194:197], v[68:71]
	v_mfma_f32_16x16x32_bf16 v[132:135], v[112:115], v[174:177], v[132:135]
	v_mfma_f32_16x16x32_bf16 v[124:127], v[140:143], v[174:177], v[124:127]
	v_mfma_f32_16x16x32_bf16 v[116:119], v[112:115], v[182:185], v[116:119]
	v_mfma_f32_16x16x32_bf16 v[104:107], v[140:143], v[182:185], v[104:107]
	v_mfma_f32_16x16x32_bf16 v[96:99], v[112:115], v[190:193], v[96:99]
	v_mfma_f32_16x16x32_bf16 v[88:91], v[140:143], v[190:193], v[88:91]
	v_mfma_f32_16x16x32_bf16 v[76:79], v[112:115], v[198:201], v[76:79]
	v_mfma_f32_16x16x32_bf16 v[68:71], v[140:143], v[198:201], v[68:71]
	s_barrier
	s_add_i32 s20, 0, 0x1c000
	s_add_i32 s21, s34, s22
	v_add_u32_e32 v169, s20, v159
	v_lshl_add_u64 v[156:157], v[156:157], 0, s[96:97]
	s_mov_b32 m0, s21
	ds_read_b128 v[232:235], v169
	ds_read_b128 v[236:239], v169 offset:1024
	ds_read_b128 v[240:243], v169 offset:2048
	ds_read_b128 v[244:247], v169 offset:3072
	global_load_lds_dwordx4 v[156:157], off
	v_lshl_add_u64 v[156:157], v[202:203], 0, s[96:97]
	s_add_i32 m0, s21, 0x2000
	s_nop 0
	global_load_lds_dwordx4 v[156:157], off
	s_barrier
	s_waitcnt lgkmcnt(0)
	s_waitcnt lgkmcnt(0)
	v_mfma_f32_16x16x32_bf16 v[128:131], v[232:235], v[170:173], v[128:131]
	v_mfma_f32_16x16x32_bf16 v[120:123], v[240:243], v[170:173], v[120:123]
	v_mfma_f32_16x16x32_bf16 v[108:111], v[232:235], v[178:181], v[108:111]
	v_mfma_f32_16x16x32_bf16 v[100:103], v[240:243], v[178:181], v[100:103]
	v_mfma_f32_16x16x32_bf16 v[92:95], v[232:235], v[186:189], v[92:95]
	v_mfma_f32_16x16x32_bf16 v[84:87], v[240:243], v[186:189], v[84:87]
	v_mfma_f32_16x16x32_bf16 v[72:75], v[232:235], v[194:197], v[72:75]
	v_mfma_f32_16x16x32_bf16 v[64:67], v[240:243], v[194:197], v[64:67]
	v_mfma_f32_16x16x32_bf16 v[128:131], v[236:239], v[174:177], v[128:131]
	v_mfma_f32_16x16x32_bf16 v[120:123], v[244:247], v[174:177], v[120:123]
	v_mfma_f32_16x16x32_bf16 v[108:111], v[236:239], v[182:185], v[108:111]
	v_mfma_f32_16x16x32_bf16 v[100:103], v[244:247], v[182:185], v[100:103]
	v_mfma_f32_16x16x32_bf16 v[92:95], v[236:239], v[190:193], v[92:95]
	v_mfma_f32_16x16x32_bf16 v[84:87], v[244:247], v[190:193], v[84:87]
	v_mfma_f32_16x16x32_bf16 v[72:75], v[236:239], v[198:201], v[72:75]
	v_mfma_f32_16x16x32_bf16 v[64:67], v[244:247], v[198:201], v[64:67]
	s_mov_b32 m0, s44
	v_lshl_add_u64 v[156:157], v[206:207], 0, s[96:97]
	s_barrier
	ds_read_b128 v[170:173], v168 offset:49152
	ds_read_b128 v[174:177], v168 offset:50176
	ds_read_b128 v[178:181], v168 offset:51200
	ds_read_b128 v[182:185], v168 offset:52224
	ds_read_b128 v[186:189], v168 offset:53248
	ds_read_b128 v[190:193], v168 offset:54272
	ds_read_b128 v[194:197], v168 offset:55296
	ds_read_b128 v[198:201], v168 offset:56320
	global_load_lds_dwordx4 v[156:157], off
	v_lshl_add_u64 v[156:157], v[248:249], 0, s[96:97]
	s_mov_b32 m0, s45
	s_nop 0
	global_load_lds_dwordx4 v[156:157], off
	s_barrier
	s_waitcnt lgkmcnt(0)
	s_waitcnt lgkmcnt(0)
	v_mfma_f32_16x16x32_bf16 v[60:63], v[80:83], v[170:173], v[60:63]
	v_mfma_f32_16x16x32_bf16 v[52:55], v[136:139], v[170:173], v[52:55]
	v_mfma_f32_16x16x32_bf16 v[44:47], v[80:83], v[178:181], v[44:47]
	v_mfma_f32_16x16x32_bf16 v[36:39], v[136:139], v[178:181], v[36:39]
	v_mfma_f32_16x16x32_bf16 v[28:31], v[80:83], v[186:189], v[28:31]
	v_mfma_f32_16x16x32_bf16 v[20:23], v[136:139], v[186:189], v[20:23]
	v_mfma_f32_16x16x32_bf16 v[12:15], v[80:83], v[194:197], v[12:15]
	v_mfma_f32_16x16x32_bf16 v[4:7], v[136:139], v[194:197], v[4:7]
	v_mfma_f32_16x16x32_bf16 v[60:63], v[112:115], v[174:177], v[60:63]
	v_mfma_f32_16x16x32_bf16 v[52:55], v[140:143], v[174:177], v[52:55]
	v_mfma_f32_16x16x32_bf16 v[44:47], v[112:115], v[182:185], v[44:47]
	v_mfma_f32_16x16x32_bf16 v[36:39], v[140:143], v[182:185], v[36:39]
	v_mfma_f32_16x16x32_bf16 v[28:31], v[112:115], v[190:193], v[28:31]
	v_mfma_f32_16x16x32_bf16 v[20:23], v[140:143], v[190:193], v[20:23]
	v_mfma_f32_16x16x32_bf16 v[12:15], v[112:115], v[198:201], v[12:15]
	v_mfma_f32_16x16x32_bf16 v[4:7], v[140:143], v[198:201], v[4:7]
	s_barrier
	s_add_i32 s20, s20, s22
	v_lshl_add_u64 v[80:81], v[250:251], 0, s[96:97]
	s_mov_b32 m0, s20
	s_nop 0
	global_load_lds_dwordx4 v[80:81], off
	v_lshl_add_u64 v[80:81], v[210:211], 0, s[96:97]
	s_add_i32 m0, s20, 0x2000
	s_nop 0
	global_load_lds_dwordx4 v[80:81], off
	s_waitcnt vmcnt(6)
	s_barrier
	v_mfma_f32_16x16x32_bf16 v[56:59], v[232:235], v[170:173], v[56:59]
	v_mfma_f32_16x16x32_bf16 v[48:51], v[240:243], v[170:173], v[48:51]
	v_mfma_f32_16x16x32_bf16 v[40:43], v[232:235], v[178:181], v[40:43]
	v_mfma_f32_16x16x32_bf16 v[32:35], v[240:243], v[178:181], v[32:35]
	v_mfma_f32_16x16x32_bf16 v[24:27], v[232:235], v[186:189], v[24:27]
	v_mfma_f32_16x16x32_bf16 v[16:19], v[240:243], v[186:189], v[16:19]
	v_mfma_f32_16x16x32_bf16 v[8:11], v[232:235], v[194:197], v[8:11]
	v_mfma_f32_16x16x32_bf16 v[0:3], v[240:243], v[194:197], v[0:3]
	v_mfma_f32_16x16x32_bf16 v[56:59], v[236:239], v[174:177], v[56:59]
	v_mfma_f32_16x16x32_bf16 v[48:51], v[244:247], v[174:177], v[48:51]
	v_mfma_f32_16x16x32_bf16 v[40:43], v[236:239], v[182:185], v[40:43]
	v_mfma_f32_16x16x32_bf16 v[32:35], v[244:247], v[182:185], v[32:35]
	v_mfma_f32_16x16x32_bf16 v[24:27], v[236:239], v[190:193], v[24:27]
	v_mfma_f32_16x16x32_bf16 v[16:19], v[244:247], v[190:193], v[16:19]
	v_mfma_f32_16x16x32_bf16 v[8:11], v[236:239], v[198:201], v[8:11]
	v_mfma_f32_16x16x32_bf16 v[0:3], v[244:247], v[198:201], v[0:3]
	s_add_u32 s25, s25, 0x100
	s_addc_u32 s38, s38, 0
	s_add_u32 s30, s30, 0x100
	s_addc_u32 s31, s31, 0
	s_cmp_ge_i32 s39, s41
	s_mov_b32 s20, s39
	s_barrier
	s_cbranch_scc0 .LBB0_678
	v_readlane_b32 s20, v254, 5
	v_readlane_b32 s21, v254, 6
.LBB0_711:
	s_lshl_b32 s25, s24, 11
	s_and_b32 s25, s25, 0x800
	v_add_u32_e32 v80, s25, v166
	ds_read2_b64 v[140:143], v80 offset1:16
	ds_read2_b64 v[136:139], v80 offset0:32 offset1:48
	ds_read2_b64 v[112:115], v80 offset0:128 offset1:144
	ds_read2_b64 v[80:83], v80 offset0:160 offset1:176
	s_and_b64 s[8:9], s[0:1], s[8:9]
	s_add_u32 s34, s20, 0xc400000
	s_addc_u32 s35, s21, 0
	s_movk_i32 s82, 0xb00
	v_lshl_add_u32 v169, s17, 8, v158
	v_lshl_or_b32 v156, s3, 7, v167
	v_mov_b32_e32 v157, 0
	v_mad_u64_u32 v[156:157], s[42:43], v169, s82, v[156:157]
	s_mov_b32 s82, 0xbfb8aa3b
	s_mov_b32 s38, 1.0
	s_mov_b32 s30, 0x6e000
	s_mov_b32 s31, 0
	v_lshl_add_u64 v[156:157], v[156:157], 1, s[34:35]
	s_mov_b32 s20, 0x16000
	s_mov_b32 s21, 0
	s_waitcnt lgkmcnt(0)
	v_ffbh_u32_e32 v186, v141
	v_ffbh_u32_e32 v187, v143
	v_ffbh_u32_e32 v188, v137
	v_ffbh_u32_e32 v189, v139
	v_ffbh_u32_e32 v190, v113
	v_ffbh_u32_e32 v191, v115
	v_ffbh_u32_e32 v192, v81
	v_ffbh_u32_e32 v193, v83
	v_min_u32_e32 v186, 32, v186
	v_min_u32_e32 v187, 32, v187
	v_min_u32_e32 v188, 32, v188
	v_min_u32_e32 v189, 32, v189
	v_min_u32_e32 v190, 32, v190
	v_min_u32_e32 v191, 32, v191
	v_min_u32_e32 v192, 32, v192
	v_min_u32_e32 v193, 32, v193
	v_lshlrev_b64 v[140:141], v186, v[140:141]
	v_lshlrev_b64 v[142:143], v187, v[142:143]
	v_lshlrev_b64 v[136:137], v188, v[136:137]
	v_lshlrev_b64 v[138:139], v189, v[138:139]
	v_lshlrev_b64 v[112:113], v190, v[112:113]
	v_lshlrev_b64 v[114:115], v191, v[114:115]
	v_lshlrev_b64 v[80:81], v192, v[80:81]
	v_lshlrev_b64 v[82:83], v193, v[82:83]
	v_min_u32_e32 v140, 1, v140
	v_min_u32_e32 v142, 1, v142
	v_min_u32_e32 v136, 1, v136
	v_min_u32_e32 v138, 1, v138
	v_min_u32_e32 v112, 1, v112
	v_min_u32_e32 v114, 1, v114
	v_min_u32_e32 v80, 1, v80
	v_min_u32_e32 v82, 1, v82
	v_or_b32_e32 v140, v141, v140
	v_or_b32_e32 v142, v143, v142
	v_or_b32_e32 v136, v137, v136
	v_or_b32_e32 v138, v139, v138
	v_or_b32_e32 v112, v113, v112
	v_or_b32_e32 v114, v115, v114
	v_or_b32_e32 v80, v81, v80
	v_or_b32_e32 v82, v83, v82
	v_cvt_f32_u32_e32 v140, v140
	v_cvt_f32_u32_e32 v142, v142
	v_cvt_f32_u32_e32 v136, v136
	v_cvt_f32_u32_e32 v138, v138
	v_cvt_f32_u32_e32 v112, v112
	v_cvt_f32_u32_e32 v114, v114
	v_cvt_f32_u32_e32 v80, v80
	v_cvt_f32_u32_e32 v82, v82
	v_sub_u32_e32 v186, 32, v186
	v_sub_u32_e32 v187, 32, v187
	v_sub_u32_e32 v188, 32, v188
	v_sub_u32_e32 v189, 32, v189
	v_sub_u32_e32 v190, 32, v190
	v_sub_u32_e32 v191, 32, v191
	v_sub_u32_e32 v192, 32, v192
	v_sub_u32_e32 v193, 32, v193
	v_ldexp_f32 v140, v140, v186
	v_ldexp_f32 v142, v142, v187
	v_ldexp_f32 v136, v136, v188
	v_ldexp_f32 v138, v138, v189
	v_ldexp_f32 v112, v112, v190
	v_ldexp_f32 v114, v114, v191
	v_ldexp_f32 v80, v80, v192
	v_ldexp_f32 v82, v82, v193
	v_mul_f32_e32 v140, 0x35800000, v140
	v_mul_f32_e32 v142, 0x35800000, v142
	v_mul_f32_e32 v136, 0x35800000, v136
	v_mul_f32_e32 v138, 0x35800000, v138
	v_mul_f32_e32 v112, 0x35800000, v112
	v_mul_f32_e32 v114, 0x35800000, v114
	v_mul_f32_e32 v80, 0x35800000, v80
	v_mul_f32_e32 v82, 0x35800000, v82
	v_fmamk_f32 v140, v140, 0x3a800000, v165
	v_fmamk_f32 v142, v142, 0x3a800000, v165
	v_fmamk_f32 v136, v136, 0x3a800000, v165
	v_fmamk_f32 v138, v138, 0x3a800000, v165
	v_fmamk_f32 v112, v112, 0x3a800000, v165
	v_fmamk_f32 v114, v114, 0x3a800000, v165
	v_fmamk_f32 v80, v80, 0x3a800000, v165
	v_fmamk_f32 v82, v82, 0x3a800000, v165
	v_rsq_f32_e32 v140, v140
	v_rsq_f32_e32 v142, v142
	v_rsq_f32_e32 v136, v136
	v_rsq_f32_e32 v138, v138
	v_rsq_f32_e32 v112, v112
	v_rsq_f32_e32 v114, v114
	v_rsq_f32_e32 v80, v80
	v_rsq_f32_e32 v82, v82
	v_pk_mul_f32 v[132:133], v[132:133], v[140:141] op_sel_hi:[1,0]
	v_pk_mul_f32 v[134:135], v[134:135], v[140:141] op_sel_hi:[1,0]
	v_pk_mul_f32 v[124:125], v[124:125], v[140:141] op_sel_hi:[1,0]
	v_pk_mul_f32 v[126:127], v[126:127], v[140:141] op_sel_hi:[1,0]
	v_pk_mul_f32 v[128:129], v[128:129], v[140:141] op_sel_hi:[1,0]
	v_pk_mul_f32 v[130:131], v[130:131], v[140:141] op_sel_hi:[1,0]
	v_pk_mul_f32 v[120:121], v[120:121], v[140:141] op_sel_hi:[1,0]
	v_pk_mul_f32 v[122:123], v[122:123], v[140:141] op_sel_hi:[1,0]
	v_pk_mul_f32 v[170:171], v[132:133], s[82:83] op_sel_hi:[1,0]
	v_pk_mul_f32 v[172:173], v[134:135], s[82:83] op_sel_hi:[1,0]
	v_pk_mul_f32 v[174:175], v[124:125], s[82:83] op_sel_hi:[1,0]
	v_pk_mul_f32 v[176:177], v[126:127], s[82:83] op_sel_hi:[1,0]
	v_exp_f32_e32 v170, v170
	v_exp_f32_e32 v171, v171
	v_exp_f32_e32 v172, v172
	v_exp_f32_e32 v173, v173
	v_exp_f32_e32 v174, v174
	v_exp_f32_e32 v175, v175
	v_exp_f32_e32 v176, v176
	v_exp_f32_e32 v177, v177
	v_pk_add_f32 v[170:171], v[170:171], s[38:39] op_sel_hi:[1,0]
	v_pk_add_f32 v[172:173], v[172:173], s[38:39] op_sel_hi:[1,0]
	v_pk_add_f32 v[174:175], v[174:175], s[38:39] op_sel_hi:[1,0]
	v_pk_add_f32 v[176:177], v[176:177], s[38:39] op_sel_hi:[1,0]
	v_rcp_f32_e32 v170, v170
	v_rcp_f32_e32 v171, v171
	v_rcp_f32_e32 v172, v172
	v_rcp_f32_e32 v173, v173
	v_rcp_f32_e32 v174, v174
	v_rcp_f32_e32 v175, v175
	v_rcp_f32_e32 v176, v176
	v_rcp_f32_e32 v177, v177
	v_pk_mul_f32 v[170:171], v[132:133], v[170:171]
	v_pk_mul_f32 v[172:173], v[134:135], v[172:173]
	v_pk_mul_f32 v[174:175], v[124:125], v[174:175]
	v_pk_mul_f32 v[176:177], v[126:127], v[176:177]
	v_pk_mul_f32 v[170:171], v[128:129], v[170:171]
	v_pk_mul_f32 v[172:173], v[130:131], v[172:173]
	v_pk_mul_f32 v[174:175], v[120:121], v[174:175]
	v_pk_mul_f32 v[176:177], v[122:123], v[176:177]
	v_cvt_pk_bf16_f32 v194, v170, v171
	v_cvt_pk_bf16_f32 v195, v172, v173
	v_cvt_pk_bf16_f32 v196, v174, v175
	v_cvt_pk_bf16_f32 v197, v176, v177
	global_store_dwordx4 v[156:157], v[194:197], off
	v_lshl_add_u64 v[156:157], v[156:157], 0, s[20:21]
	v_pk_mul_f32 v[116:117], v[116:117], v[142:143] op_sel_hi:[1,0]
	v_pk_mul_f32 v[118:119], v[118:119], v[142:143] op_sel_hi:[1,0]
	v_pk_mul_f32 v[104:105], v[104:105], v[142:143] op_sel_hi:[1,0]
	v_pk_mul_f32 v[106:107], v[106:107], v[142:143] op_sel_hi:[1,0]
	v_pk_mul_f32 v[108:109], v[108:109], v[142:143] op_sel_hi:[1,0]
	v_pk_mul_f32 v[110:111], v[110:111], v[142:143] op_sel_hi:[1,0]
	v_pk_mul_f32 v[100:101], v[100:101], v[142:143] op_sel_hi:[1,0]
	v_pk_mul_f32 v[102:103], v[102:103], v[142:143] op_sel_hi:[1,0]
	v_pk_mul_f32 v[178:179], v[116:117], s[82:83] op_sel_hi:[1,0]
	v_pk_mul_f32 v[180:181], v[118:119], s[82:83] op_sel_hi:[1,0]
	v_pk_mul_f32 v[182:183], v[104:105], s[82:83] op_sel_hi:[1,0]
	v_pk_mul_f32 v[184:185], v[106:107], s[82:83] op_sel_hi:[1,0]
	v_exp_f32_e32 v178, v178
	v_exp_f32_e32 v179, v179
	v_exp_f32_e32 v180, v180
	v_exp_f32_e32 v181, v181
	v_exp_f32_e32 v182, v182
	v_exp_f32_e32 v183, v183
	v_exp_f32_e32 v184, v184
	v_exp_f32_e32 v185, v185
	v_pk_add_f32 v[178:179], v[178:179], s[38:39] op_sel_hi:[1,0]
	v_pk_add_f32 v[180:181], v[180:181], s[38:39] op_sel_hi:[1,0]
	v_pk_add_f32 v[182:183], v[182:183], s[38:39] op_sel_hi:[1,0]
	v_pk_add_f32 v[184:185], v[184:185], s[38:39] op_sel_hi:[1,0]
	v_rcp_f32_e32 v178, v178
	v_rcp_f32_e32 v179, v179
	v_rcp_f32_e32 v180, v180
	v_rcp_f32_e32 v181, v181
	v_rcp_f32_e32 v182, v182
	v_rcp_f32_e32 v183, v183
	v_rcp_f32_e32 v184, v184
	v_rcp_f32_e32 v185, v185
	v_pk_mul_f32 v[178:179], v[116:117], v[178:179]
	v_pk_mul_f32 v[180:181], v[118:119], v[180:181]
	v_pk_mul_f32 v[182:183], v[104:105], v[182:183]
	v_pk_mul_f32 v[184:185], v[106:107], v[184:185]
	v_pk_mul_f32 v[178:179], v[108:109], v[178:179]
	v_pk_mul_f32 v[180:181], v[110:111], v[180:181]
	v_pk_mul_f32 v[182:183], v[100:101], v[182:183]
	v_pk_mul_f32 v[184:185], v[102:103], v[184:185]
	v_cvt_pk_bf16_f32 v198, v178, v179
	v_cvt_pk_bf16_f32 v199, v180, v181
	v_cvt_pk_bf16_f32 v200, v182, v183
	v_cvt_pk_bf16_f32 v201, v184, v185
	global_store_dwordx4 v[156:157], v[198:201], off
	v_lshl_add_u64 v[156:157], v[156:157], 0, s[20:21]
	v_pk_mul_f32 v[96:97], v[96:97], v[136:137] op_sel_hi:[1,0]
	v_pk_mul_f32 v[98:99], v[98:99], v[136:137] op_sel_hi:[1,0]
	v_pk_mul_f32 v[88:89], v[88:89], v[136:137] op_sel_hi:[1,0]
	v_pk_mul_f32 v[90:91], v[90:91], v[136:137] op_sel_hi:[1,0]
	v_pk_mul_f32 v[92:93], v[92:93], v[136:137] op_sel_hi:[1,0]
	v_pk_mul_f32 v[94:95], v[94:95], v[136:137] op_sel_hi:[1,0]
	v_pk_mul_f32 v[84:85], v[84:85], v[136:137] op_sel_hi:[1,0]
	v_pk_mul_f32 v[86:87], v[86:87], v[136:137] op_sel_hi:[1,0]
	v_pk_mul_f32 v[170:171], v[96:97], s[82:83] op_sel_hi:[1,0]
	v_pk_mul_f32 v[172:173], v[98:99], s[82:83] op_sel_hi:[1,0]
	v_pk_mul_f32 v[174:175], v[88:89], s[82:83] op_sel_hi:[1,0]
	v_pk_mul_f32 v[176:177], v[90:91], s[82:83] op_sel_hi:[1,0]
	v_exp_f32_e32 v170, v170
	v_exp_f32_e32 v171, v171
	v_exp_f32_e32 v172, v172
	v_exp_f32_e32 v173, v173
	v_exp_f32_e32 v174, v174
	v_exp_f32_e32 v175, v175
	v_exp_f32_e32 v176, v176
	v_exp_f32_e32 v177, v177
	v_pk_add_f32 v[170:171], v[170:171], s[38:39] op_sel_hi:[1,0]
	v_pk_add_f32 v[172:173], v[172:173], s[38:39] op_sel_hi:[1,0]
	v_pk_add_f32 v[174:175], v[174:175], s[38:39] op_sel_hi:[1,0]
	v_pk_add_f32 v[176:177], v[176:177], s[38:39] op_sel_hi:[1,0]
	v_rcp_f32_e32 v170, v170
	v_rcp_f32_e32 v171, v171
	v_rcp_f32_e32 v172, v172
	v_rcp_f32_e32 v173, v173
	v_rcp_f32_e32 v174, v174
	v_rcp_f32_e32 v175, v175
	v_rcp_f32_e32 v176, v176
	v_rcp_f32_e32 v177, v177
	v_pk_mul_f32 v[170:171], v[96:97], v[170:171]
	v_pk_mul_f32 v[172:173], v[98:99], v[172:173]
	v_pk_mul_f32 v[174:175], v[88:89], v[174:175]
	v_pk_mul_f32 v[176:177], v[90:91], v[176:177]
	v_pk_mul_f32 v[170:171], v[92:93], v[170:171]
	v_pk_mul_f32 v[172:173], v[94:95], v[172:173]
	v_pk_mul_f32 v[174:175], v[84:85], v[174:175]
	v_pk_mul_f32 v[176:177], v[86:87], v[176:177]
	v_cvt_pk_bf16_f32 v194, v170, v171
	v_cvt_pk_bf16_f32 v195, v172, v173
	v_cvt_pk_bf16_f32 v196, v174, v175
	v_cvt_pk_bf16_f32 v197, v176, v177
	global_store_dwordx4 v[156:157], v[194:197], off
	v_lshl_add_u64 v[156:157], v[156:157], 0, s[20:21]
	v_pk_mul_f32 v[76:77], v[76:77], v[138:139] op_sel_hi:[1,0]
	v_pk_mul_f32 v[78:79], v[78:79], v[138:139] op_sel_hi:[1,0]
	v_pk_mul_f32 v[68:69], v[68:69], v[138:139] op_sel_hi:[1,0]
	v_pk_mul_f32 v[70:71], v[70:71], v[138:139] op_sel_hi:[1,0]
	v_pk_mul_f32 v[72:73], v[72:73], v[138:139] op_sel_hi:[1,0]
	v_pk_mul_f32 v[74:75], v[74:75], v[138:139] op_sel_hi:[1,0]
	v_pk_mul_f32 v[64:65], v[64:65], v[138:139] op_sel_hi:[1,0]
	v_pk_mul_f32 v[66:67], v[66:67], v[138:139] op_sel_hi:[1,0]
	v_pk_mul_f32 v[178:179], v[76:77], s[82:83] op_sel_hi:[1,0]
	v_pk_mul_f32 v[180:181], v[78:79], s[82:83] op_sel_hi:[1,0]
	v_pk_mul_f32 v[182:183], v[68:69], s[82:83] op_sel_hi:[1,0]
	v_pk_mul_f32 v[184:185], v[70:71], s[82:83] op_sel_hi:[1,0]
	v_exp_f32_e32 v178, v178
	v_exp_f32_e32 v179, v179
	v_exp_f32_e32 v180, v180
	v_exp_f32_e32 v181, v181
	v_exp_f32_e32 v182, v182
	v_exp_f32_e32 v183, v183
	v_exp_f32_e32 v184, v184
	v_exp_f32_e32 v185, v185
	v_pk_add_f32 v[178:179], v[178:179], s[38:39] op_sel_hi:[1,0]
	v_pk_add_f32 v[180:181], v[180:181], s[38:39] op_sel_hi:[1,0]
	v_pk_add_f32 v[182:183], v[182:183], s[38:39] op_sel_hi:[1,0]
	v_pk_add_f32 v[184:185], v[184:185], s[38:39] op_sel_hi:[1,0]
	v_rcp_f32_e32 v178, v178
	v_rcp_f32_e32 v179, v179
	v_rcp_f32_e32 v180, v180
	v_rcp_f32_e32 v181, v181
	v_rcp_f32_e32 v182, v182
	v_rcp_f32_e32 v183, v183
	v_rcp_f32_e32 v184, v184
	v_rcp_f32_e32 v185, v185
	v_pk_mul_f32 v[178:179], v[76:77], v[178:179]
	v_pk_mul_f32 v[180:181], v[78:79], v[180:181]
	v_pk_mul_f32 v[182:183], v[68:69], v[182:183]
	v_pk_mul_f32 v[184:185], v[70:71], v[184:185]
	v_pk_mul_f32 v[178:179], v[72:73], v[178:179]
	v_pk_mul_f32 v[180:181], v[74:75], v[180:181]
	v_pk_mul_f32 v[182:183], v[64:65], v[182:183]
	v_pk_mul_f32 v[184:185], v[66:67], v[184:185]
	v_cvt_pk_bf16_f32 v198, v178, v179
	v_cvt_pk_bf16_f32 v199, v180, v181
	v_cvt_pk_bf16_f32 v200, v182, v183
	v_cvt_pk_bf16_f32 v201, v184, v185
	global_store_dwordx4 v[156:157], v[198:201], off
	v_lshl_add_u64 v[156:157], v[156:157], 0, s[30:31]
	v_pk_mul_f32 v[60:61], v[60:61], v[112:113] op_sel_hi:[1,0]
	v_pk_mul_f32 v[62:63], v[62:63], v[112:113] op_sel_hi:[1,0]
	v_pk_mul_f32 v[52:53], v[52:53], v[112:113] op_sel_hi:[1,0]
	v_pk_mul_f32 v[54:55], v[54:55], v[112:113] op_sel_hi:[1,0]
	v_pk_mul_f32 v[56:57], v[56:57], v[112:113] op_sel_hi:[1,0]
	v_pk_mul_f32 v[58:59], v[58:59], v[112:113] op_sel_hi:[1,0]
	v_pk_mul_f32 v[48:49], v[48:49], v[112:113] op_sel_hi:[1,0]
	v_pk_mul_f32 v[50:51], v[50:51], v[112:113] op_sel_hi:[1,0]
	v_pk_mul_f32 v[170:171], v[60:61], s[82:83] op_sel_hi:[1,0]
	v_pk_mul_f32 v[172:173], v[62:63], s[82:83] op_sel_hi:[1,0]
	v_pk_mul_f32 v[174:175], v[52:53], s[82:83] op_sel_hi:[1,0]
	v_pk_mul_f32 v[176:177], v[54:55], s[82:83] op_sel_hi:[1,0]
	v_exp_f32_e32 v170, v170
	v_exp_f32_e32 v171, v171
	v_exp_f32_e32 v172, v172
	v_exp_f32_e32 v173, v173
	v_exp_f32_e32 v174, v174
	v_exp_f32_e32 v175, v175
	v_exp_f32_e32 v176, v176
	v_exp_f32_e32 v177, v177
	v_pk_add_f32 v[170:171], v[170:171], s[38:39] op_sel_hi:[1,0]
	v_pk_add_f32 v[172:173], v[172:173], s[38:39] op_sel_hi:[1,0]
	v_pk_add_f32 v[174:175], v[174:175], s[38:39] op_sel_hi:[1,0]
	v_pk_add_f32 v[176:177], v[176:177], s[38:39] op_sel_hi:[1,0]
	v_rcp_f32_e32 v170, v170
	v_rcp_f32_e32 v171, v171
	v_rcp_f32_e32 v172, v172
	v_rcp_f32_e32 v173, v173
	v_rcp_f32_e32 v174, v174
	v_rcp_f32_e32 v175, v175
	v_rcp_f32_e32 v176, v176
	v_rcp_f32_e32 v177, v177
	v_pk_mul_f32 v[170:171], v[60:61], v[170:171]
	v_pk_mul_f32 v[172:173], v[62:63], v[172:173]
	v_pk_mul_f32 v[174:175], v[52:53], v[174:175]
	v_pk_mul_f32 v[176:177], v[54:55], v[176:177]
	v_pk_mul_f32 v[170:171], v[56:57], v[170:171]
	v_pk_mul_f32 v[172:173], v[58:59], v[172:173]
	v_pk_mul_f32 v[174:175], v[48:49], v[174:175]
	v_pk_mul_f32 v[176:177], v[50:51], v[176:177]
	v_cvt_pk_bf16_f32 v194, v170, v171
	v_cvt_pk_bf16_f32 v195, v172, v173
	v_cvt_pk_bf16_f32 v196, v174, v175
	v_cvt_pk_bf16_f32 v197, v176, v177
	global_store_dwordx4 v[156:157], v[194:197], off
	v_lshl_add_u64 v[156:157], v[156:157], 0, s[20:21]
	v_pk_mul_f32 v[44:45], v[44:45], v[114:115] op_sel_hi:[1,0]
	v_pk_mul_f32 v[46:47], v[46:47], v[114:115] op_sel_hi:[1,0]
	v_pk_mul_f32 v[36:37], v[36:37], v[114:115] op_sel_hi:[1,0]
	v_pk_mul_f32 v[38:39], v[38:39], v[114:115] op_sel_hi:[1,0]
	v_pk_mul_f32 v[40:41], v[40:41], v[114:115] op_sel_hi:[1,0]
	v_pk_mul_f32 v[42:43], v[42:43], v[114:115] op_sel_hi:[1,0]
	v_pk_mul_f32 v[32:33], v[32:33], v[114:115] op_sel_hi:[1,0]
	v_pk_mul_f32 v[34:35], v[34:35], v[114:115] op_sel_hi:[1,0]
	v_pk_mul_f32 v[178:179], v[44:45], s[82:83] op_sel_hi:[1,0]
	v_pk_mul_f32 v[180:181], v[46:47], s[82:83] op_sel_hi:[1,0]
	v_pk_mul_f32 v[182:183], v[36:37], s[82:83] op_sel_hi:[1,0]
	v_pk_mul_f32 v[184:185], v[38:39], s[82:83] op_sel_hi:[1,0]
	v_exp_f32_e32 v178, v178
	v_exp_f32_e32 v179, v179
	v_exp_f32_e32 v180, v180
	v_exp_f32_e32 v181, v181
	v_exp_f32_e32 v182, v182
	v_exp_f32_e32 v183, v183
	v_exp_f32_e32 v184, v184
	v_exp_f32_e32 v185, v185
	v_pk_add_f32 v[178:179], v[178:179], s[38:39] op_sel_hi:[1,0]
	v_pk_add_f32 v[180:181], v[180:181], s[38:39] op_sel_hi:[1,0]
	v_pk_add_f32 v[182:183], v[182:183], s[38:39] op_sel_hi:[1,0]
	v_pk_add_f32 v[184:185], v[184:185], s[38:39] op_sel_hi:[1,0]
	v_rcp_f32_e32 v178, v178
	v_rcp_f32_e32 v179, v179
	v_rcp_f32_e32 v180, v180
	v_rcp_f32_e32 v181, v181
	v_rcp_f32_e32 v182, v182
	v_rcp_f32_e32 v183, v183
	v_rcp_f32_e32 v184, v184
	v_rcp_f32_e32 v185, v185
	v_pk_mul_f32 v[178:179], v[44:45], v[178:179]
	v_pk_mul_f32 v[180:181], v[46:47], v[180:181]
	v_pk_mul_f32 v[182:183], v[36:37], v[182:183]
	v_pk_mul_f32 v[184:185], v[38:39], v[184:185]
	v_pk_mul_f32 v[178:179], v[40:41], v[178:179]
	v_pk_mul_f32 v[180:181], v[42:43], v[180:181]
	v_pk_mul_f32 v[182:183], v[32:33], v[182:183]
	v_pk_mul_f32 v[184:185], v[34:35], v[184:185]
	v_cvt_pk_bf16_f32 v198, v178, v179
	v_cvt_pk_bf16_f32 v199, v180, v181
	v_cvt_pk_bf16_f32 v200, v182, v183
	v_cvt_pk_bf16_f32 v201, v184, v185
	global_store_dwordx4 v[156:157], v[198:201], off
	v_lshl_add_u64 v[156:157], v[156:157], 0, s[20:21]
	v_pk_mul_f32 v[28:29], v[28:29], v[80:81] op_sel_hi:[1,0]
	v_pk_mul_f32 v[30:31], v[30:31], v[80:81] op_sel_hi:[1,0]
	v_pk_mul_f32 v[20:21], v[20:21], v[80:81] op_sel_hi:[1,0]
	v_pk_mul_f32 v[22:23], v[22:23], v[80:81] op_sel_hi:[1,0]
	v_pk_mul_f32 v[24:25], v[24:25], v[80:81] op_sel_hi:[1,0]
	v_pk_mul_f32 v[26:27], v[26:27], v[80:81] op_sel_hi:[1,0]
	v_pk_mul_f32 v[16:17], v[16:17], v[80:81] op_sel_hi:[1,0]
	v_pk_mul_f32 v[18:19], v[18:19], v[80:81] op_sel_hi:[1,0]
	v_pk_mul_f32 v[170:171], v[28:29], s[82:83] op_sel_hi:[1,0]
	v_pk_mul_f32 v[172:173], v[30:31], s[82:83] op_sel_hi:[1,0]
	v_pk_mul_f32 v[174:175], v[20:21], s[82:83] op_sel_hi:[1,0]
	v_pk_mul_f32 v[176:177], v[22:23], s[82:83] op_sel_hi:[1,0]
	v_exp_f32_e32 v170, v170
	v_exp_f32_e32 v171, v171
	v_exp_f32_e32 v172, v172
	v_exp_f32_e32 v173, v173
	v_exp_f32_e32 v174, v174
	v_exp_f32_e32 v175, v175
	v_exp_f32_e32 v176, v176
	v_exp_f32_e32 v177, v177
	v_pk_add_f32 v[170:171], v[170:171], s[38:39] op_sel_hi:[1,0]
	v_pk_add_f32 v[172:173], v[172:173], s[38:39] op_sel_hi:[1,0]
	v_pk_add_f32 v[174:175], v[174:175], s[38:39] op_sel_hi:[1,0]
	v_pk_add_f32 v[176:177], v[176:177], s[38:39] op_sel_hi:[1,0]
	v_rcp_f32_e32 v170, v170
	v_rcp_f32_e32 v171, v171
	v_rcp_f32_e32 v172, v172
	v_rcp_f32_e32 v173, v173
	v_rcp_f32_e32 v174, v174
	v_rcp_f32_e32 v175, v175
	v_rcp_f32_e32 v176, v176
	v_rcp_f32_e32 v177, v177
	v_pk_mul_f32 v[170:171], v[28:29], v[170:171]
	v_pk_mul_f32 v[172:173], v[30:31], v[172:173]
	v_pk_mul_f32 v[174:175], v[20:21], v[174:175]
	v_pk_mul_f32 v[176:177], v[22:23], v[176:177]
	v_pk_mul_f32 v[170:171], v[24:25], v[170:171]
	v_pk_mul_f32 v[172:173], v[26:27], v[172:173]
	v_pk_mul_f32 v[174:175], v[16:17], v[174:175]
	v_pk_mul_f32 v[176:177], v[18:19], v[176:177]
	v_cvt_pk_bf16_f32 v194, v170, v171
	v_cvt_pk_bf16_f32 v195, v172, v173
	v_cvt_pk_bf16_f32 v196, v174, v175
	v_cvt_pk_bf16_f32 v197, v176, v177
	global_store_dwordx4 v[156:157], v[194:197], off
	v_lshl_add_u64 v[156:157], v[156:157], 0, s[20:21]
	v_pk_mul_f32 v[12:13], v[12:13], v[82:83] op_sel_hi:[1,0]
	v_pk_mul_f32 v[14:15], v[14:15], v[82:83] op_sel_hi:[1,0]
	v_pk_mul_f32 v[4:5], v[4:5], v[82:83] op_sel_hi:[1,0]
	v_pk_mul_f32 v[6:7], v[6:7], v[82:83] op_sel_hi:[1,0]
	v_pk_mul_f32 v[8:9], v[8:9], v[82:83] op_sel_hi:[1,0]
	v_pk_mul_f32 v[10:11], v[10:11], v[82:83] op_sel_hi:[1,0]
	v_pk_mul_f32 v[0:1], v[0:1], v[82:83] op_sel_hi:[1,0]
	v_pk_mul_f32 v[2:3], v[2:3], v[82:83] op_sel_hi:[1,0]
	v_pk_mul_f32 v[178:179], v[12:13], s[82:83] op_sel_hi:[1,0]
	v_pk_mul_f32 v[180:181], v[14:15], s[82:83] op_sel_hi:[1,0]
	v_pk_mul_f32 v[182:183], v[4:5], s[82:83] op_sel_hi:[1,0]
	v_pk_mul_f32 v[184:185], v[6:7], s[82:83] op_sel_hi:[1,0]
	v_exp_f32_e32 v178, v178
	v_exp_f32_e32 v179, v179
	v_exp_f32_e32 v180, v180
	v_exp_f32_e32 v181, v181
	v_exp_f32_e32 v182, v182
	v_exp_f32_e32 v183, v183
	v_exp_f32_e32 v184, v184
	v_exp_f32_e32 v185, v185
	v_pk_add_f32 v[178:179], v[178:179], s[38:39] op_sel_hi:[1,0]
	v_pk_add_f32 v[180:181], v[180:181], s[38:39] op_sel_hi:[1,0]
	v_pk_add_f32 v[182:183], v[182:183], s[38:39] op_sel_hi:[1,0]
	v_pk_add_f32 v[184:185], v[184:185], s[38:39] op_sel_hi:[1,0]
	v_rcp_f32_e32 v178, v178
	v_rcp_f32_e32 v179, v179
	v_rcp_f32_e32 v180, v180
	v_rcp_f32_e32 v181, v181
	v_rcp_f32_e32 v182, v182
	v_rcp_f32_e32 v183, v183
	v_rcp_f32_e32 v184, v184
	v_rcp_f32_e32 v185, v185
	v_pk_mul_f32 v[178:179], v[12:13], v[178:179]
	v_pk_mul_f32 v[180:181], v[14:15], v[180:181]
	v_pk_mul_f32 v[182:183], v[4:5], v[182:183]
	v_pk_mul_f32 v[184:185], v[6:7], v[184:185]
	v_pk_mul_f32 v[178:179], v[8:9], v[178:179]
	v_pk_mul_f32 v[180:181], v[10:11], v[180:181]
	v_pk_mul_f32 v[182:183], v[0:1], v[182:183]
	v_pk_mul_f32 v[184:185], v[2:3], v[184:185]
	v_cvt_pk_bf16_f32 v198, v178, v179
	v_cvt_pk_bf16_f32 v199, v180, v181
	v_cvt_pk_bf16_f32 v200, v182, v183
	v_cvt_pk_bf16_f32 v201, v184, v185
	global_store_dwordx4 v[156:157], v[198:201], off
	s_and_b64 vcc, exec, s[8:9]
	s_cbranch_vccz .LBB0_666
	s_lshl_b32 s8, s16, 8
	s_lshl_b32 s3, s94, 11
	s_ashr_i32 s9, s8, 31
	s_and_b32 s3, s3, 0x800
	v_lshl_add_u64 v[0:1], s[8:9], 3, v[150:151]
	s_add_i32 m0, s46, s3
	s_nop 0
	global_load_lds_dwordx4 v[0:1], off
	s_branch .LBB0_666
	s_nop 0
	s_nop 0
	s_nop 0
	s_nop 0
	s_nop 0
	s_nop 0
	s_nop 0
	s_nop 0
	s_nop 0
	s_nop 0
	s_nop 0
	s_nop 0
	s_nop 0
	s_nop 0
	s_nop 0
	s_nop 0
	s_nop 0
	s_nop 0
	s_nop 0
	s_nop 0
	s_nop 0
	s_nop 0
	s_nop 0
	s_nop 0
